# mixer SGU part rewritten by hand: causal W fragments masked once, LDS fragment reads batched and double-buffered per half chunk, one wait for the u rows
# speedup vs baseline: 1.0157x; 1.0157x over previous
; __device__ __forceinline__ unsigned pkbf(float lo, float hi) { typedef float f2_t __attribute__((ext_vector_type(2))); typedef __bf16 b2_t __attribute__((ext_vector_type(2))); f2_t v = {lo, hi}; b2_t b = __builtin_convertvector(v, b2_t); return __builtin_bit_cast(unsigned, b); }
; __device__ __forceinline__ float bflo(unsigned w) { return __uint_as_float(w << 16); }
; __device__ __forceinline__ float bfhi(unsigned w) { return __uint_as_float(w & 0xffff0000u); }
; __device__ __forceinline__ void mixer_phase256(const Args& A, int l, int vc, const bf16* Z, bf16* MIX, ss_t* ssa, ss_t* ssb, unsigned char* lds, int tid, int wid, int lane) {
;     ...
;     { const float* gs = A.sgu_norm_g + (l * 16 + h) * 64; float ss = 0.f; bf16* vn = VN + sj * 64 * VN_STRIDE;
; #pragma unroll
;       for (int c = 0; c < 8; ++c)
; #pragma unroll
;           for (int e = 0; e < 4; ++e) { const float a = bflo(sw[c][e]), b = bfhi(sw[c][e]); ss += a * a + b * b; }
;       const float rstd = 1.0f / sqrtf(ss * (1.0f / 64.f) + EPS);
; #pragma unroll
;       for (int c = 0; c < 8; ++c) { const f32x4 g0 = *(const f32x4*)(gs + 8 * c), g1 = *(const f32x4*)(gs + 8 * c + 4); const float gg[8] = {g0.x, g0.y, g0.z, g0.w, g1.x, g1.y, g1.z, g1.w};
; #pragma unroll
;           for (int e = 0; e < 4; ++e) { const unsigned w = pkbf(bflo(sw[c][e]) * rstd * gg[2 * e], bfhi(sw[c][e]) * rstd * gg[2 * e + 1]);
;               vn[(8 * c + 2 * e) * VN_STRIDE + srow] = (bf16)(w & 0xffffu); vn[(8 * c + 2 * e + 1) * VN_STRIDE + srow] = (bf16)(w >> 16); } }
.LBB0_520:
	s_or_b64 exec, exec, s[12:13]
	v_and_b32_e32 v91, 0xffff0000, v65
	v_and_b32_e32 v90, 0xffff0000, v64
	s_lshl_b32 s76, s38, 6
	s_movk_i32 s2, 0x4400
	v_lshlrev_b32_e32 v89, 16, v65
	v_lshlrev_b32_e32 v88, 16, v64
	v_pk_mul_f32 v[0:1], v[90:91], v[90:91]
	v_and_b32_e32 v87, 0xffff0000, v67
	v_and_b32_e32 v86, 0xffff0000, v66
	v_mul_lo_u32 v77, v177, s2
	v_pk_fma_f32 v[104:105], v[88:89], v[88:89], v[0:1]
	v_lshlrev_b32_e32 v85, 16, v67
	v_lshlrev_b32_e32 v84, 16, v66
	v_pk_mul_f32 v[0:1], v[86:87], v[86:87]
	v_and_b32_e32 v83, 0xffff0000, v61
	v_and_b32_e32 v82, 0xffff0000, v60
	s_lshl_b64 s[2:3], s[76:77], 2
	v_pk_fma_f32 v[106:107], v[84:85], v[84:85], v[0:1]
	v_lshlrev_b32_e32 v81, 16, v61
	v_lshlrev_b32_e32 v80, 16, v60
	v_pk_mul_f32 v[0:1], v[82:83], v[82:83]
	v_and_b32_e32 v79, 0xffff0000, v63
	v_and_b32_e32 v78, 0xffff0000, v62
	s_add_u32 s12, s48, s2
	v_pk_fma_f32 v[108:109], v[80:81], v[80:81], v[0:1]
	v_lshlrev_b32_e32 v1, 16, v63
	v_lshlrev_b32_e32 v0, 16, v62
	v_pk_mul_f32 v[60:61], v[78:79], v[78:79]
	s_addc_u32 s13, s49, s3
	v_pk_fma_f32 v[110:111], v[0:1], v[0:1], v[60:61]
	global_load_dwordx4 v[60:63], v2, s[12:13] offset:48
	global_load_dwordx4 v[64:67], v2, s[12:13] offset:32
	global_load_dwordx4 v[68:71], v2, s[12:13] offset:16
	global_load_dwordx4 v[72:75], v2, s[12:13]
	v_lshlrev_b32_e32 v136, 16, v56
	v_and_b32_e32 v137, 0xffff0000, v56
	v_lshlrev_b32_e32 v138, 16, v57
	v_and_b32_e32 v139, 0xffff0000, v57
	v_pk_mul_f32 v[116:117], v[136:137], v[136:137]
	v_pk_mul_f32 v[118:119], v[138:139], v[138:139]
	v_lshlrev_b32_e32 v140, 16, v58
	v_and_b32_e32 v141, 0xffff0000, v58
	v_pk_mul_f32 v[120:121], v[140:141], v[140:141]
	v_lshlrev_b32_e32 v142, 16, v59
	v_and_b32_e32 v143, 0xffff0000, v59
	v_add_f32_e32 v118, v118, v119
	v_add_f32_e32 v116, v116, v117
	v_pk_mul_f32 v[122:123], v[142:143], v[142:143]
	v_lshlrev_b32_e32 v144, 16, v52
	v_and_b32_e32 v145, 0xffff0000, v52
	v_add_f32_e32 v116, v116, v118
	v_add_f32_e32 v117, v120, v121
	v_pk_mul_f32 v[124:125], v[144:145], v[144:145]
	v_lshlrev_b32_e32 v146, 16, v53
	v_and_b32_e32 v147, 0xffff0000, v53
	v_add_f32_e32 v115, v122, v123
	v_add_f32_e32 v116, v117, v116
	v_pk_mul_f32 v[126:127], v[146:147], v[146:147]
	v_lshlrev_b32_e32 v148, 16, v54
	v_and_b32_e32 v149, 0xffff0000, v54
	v_add_f32_e32 v115, v115, v116
	v_add_f32_e32 v116, v124, v125
	v_pk_mul_f32 v[128:129], v[148:149], v[148:149]
	v_lshlrev_b32_e32 v150, 16, v55
	v_and_b32_e32 v151, 0xffff0000, v55
	v_add_f32_e32 v115, v116, v115
	v_add_f32_e32 v116, v126, v127
	v_pk_mul_f32 v[130:131], v[150:151], v[150:151]
	v_lshlrev_b32_e32 v152, 16, v48
	v_and_b32_e32 v153, 0xffff0000, v48
	v_add_f32_e32 v115, v116, v115
	v_add_f32_e32 v116, v128, v129
	v_pk_mul_f32 v[132:133], v[152:153], v[152:153]
	v_lshlrev_b32_e32 v154, 16, v49
	v_and_b32_e32 v155, 0xffff0000, v49
	v_add_f32_e32 v115, v116, v115
	v_add_f32_e32 v116, v130, v131
	v_pk_mul_f32 v[134:135], v[154:155], v[154:155]
	v_lshlrev_b32_e32 v92, 16, v50
	v_and_b32_e32 v93, 0xffff0000, v50
	v_add_f32_e32 v115, v116, v115
	v_add_f32_e32 v116, v132, v133
	v_pk_mul_f32 v[156:157], v[92:93], v[92:93]
	v_lshlrev_b32_e32 v48, 16, v51
	v_and_b32_e32 v49, 0xffff0000, v51
	v_add_f32_e32 v115, v116, v115
	v_add_f32_e32 v116, v134, v135
	v_pk_mul_f32 v[158:159], v[48:49], v[48:49]
	v_lshlrev_b32_e32 v96, 16, v44
	v_and_b32_e32 v97, 0xffff0000, v44
	v_add_f32_e32 v115, v116, v115
	v_add_f32_e32 v116, v156, v157
	v_pk_mul_f32 v[172:173], v[96:97], v[96:97]
	v_lshlrev_b32_e32 v94, 16, v45
	v_and_b32_e32 v95, 0xffff0000, v45
	v_add_f32_e32 v115, v116, v115
	v_add_f32_e32 v116, v158, v159
	v_pk_mul_f32 v[178:179], v[94:95], v[94:95]
	v_lshlrev_b32_e32 v50, 16, v46
	v_and_b32_e32 v51, 0xffff0000, v46
	v_add_f32_e32 v115, v116, v115
	v_add_f32_e32 v116, v172, v173
	v_pk_mul_f32 v[180:181], v[50:51], v[50:51]
	v_lshlrev_b32_e32 v44, 16, v47
	v_and_b32_e32 v45, 0xffff0000, v47
	v_add_f32_e32 v115, v116, v115
	v_add_f32_e32 v116, v178, v179
	v_pk_mul_f32 v[182:183], v[44:45], v[44:45]
	v_lshlrev_b32_e32 v46, 16, v8
	v_and_b32_e32 v47, 0xffff0000, v8
	v_add_f32_e32 v115, v116, v115
	v_add_f32_e32 v116, v180, v181
	v_pk_mul_f32 v[184:185], v[46:47], v[46:47]
	v_lshlrev_b32_e32 v8, 16, v9
	v_and_b32_e32 v9, 0xffff0000, v9
	v_add_f32_e32 v115, v116, v115
	v_add_f32_e32 v116, v182, v183
	v_pk_mul_f32 v[186:187], v[8:9], v[8:9]
	v_lshlrev_b32_e32 v98, 16, v10
	v_and_b32_e32 v99, 0xffff0000, v10
	v_add_f32_e32 v115, v116, v115
	v_add_f32_e32 v116, v184, v185
	v_pk_mul_f32 v[188:189], v[98:99], v[98:99]
	v_lshlrev_b32_e32 v10, 16, v11
	v_and_b32_e32 v11, 0xffff0000, v11
	v_add_f32_e32 v115, v116, v115
	v_add_f32_e32 v116, v186, v187
	v_pk_mul_f32 v[190:191], v[10:11], v[10:11]
	v_lshlrev_b32_e32 v100, 16, v4
	v_and_b32_e32 v101, 0xffff0000, v4
	v_add_f32_e32 v115, v116, v115
	v_add_f32_e32 v116, v188, v189
	global_load_dwordx4 v[52:55], v2, s[12:13] offset:80
	global_load_dwordx4 v[56:59], v2, s[12:13] offset:64
	v_pk_mul_f32 v[192:193], v[100:101], v[100:101]
	v_lshlrev_b32_e32 v4, 16, v5
	v_and_b32_e32 v5, 0xffff0000, v5
	v_add_f32_e32 v115, v116, v115
	v_add_f32_e32 v116, v190, v191
	v_pk_mul_f32 v[194:195], v[4:5], v[4:5]
	v_lshlrev_b32_e32 v102, 16, v6
	v_and_b32_e32 v103, 0xffff0000, v6
	v_add_f32_e32 v115, v116, v115
	v_add_f32_e32 v116, v192, v193
	v_pk_mul_f32 v[196:197], v[102:103], v[102:103]
	v_lshlrev_b32_e32 v6, 16, v7
	v_and_b32_e32 v7, 0xffff0000, v7
	v_add_f32_e32 v115, v116, v115
	v_add_f32_e32 v116, v194, v195
	v_pk_mul_f32 v[198:199], v[6:7], v[6:7]
	v_add_f32_e32 v115, v116, v115
	v_add_f32_e32 v116, v196, v197
	v_add_f32_e32 v115, v116, v115
; __device__ __forceinline__ unsigned pkbf(float lo, float hi) { typedef float f2_t __attribute__((ext_vector_type(2))); typedef __bf16 b2_t __attribute__((ext_vector_type(2))); f2_t v = {lo, hi}; b2_t b = __builtin_convertvector(v, b2_t); return __builtin_bit_cast(unsigned, b); }
; __device__ __forceinline__ float bflo(unsigned w) { return __uint_as_float(w << 16); }
; __device__ __forceinline__ float bfhi(unsigned w) { return __uint_as_float(w & 0xffff0000u); }
; __device__ __forceinline__ void mixer_phase256(const Args& A, int l, int vc, const bf16* Z, bf16* MIX, ss_t* ssa, ss_t* ssb, unsigned char* lds, int tid, int wid, int lane) {
;     ...
;       const float rstd = 1.0f / sqrtf(ss * (1.0f / 64.f) + EPS);
; #pragma unroll
;       for (int c = 0; c < 8; ++c) { const f32x4 g0 = *(const f32x4*)(gs + 8 * c), g1 = *(const f32x4*)(gs + 8 * c + 4); const float gg[8] = {g0.x, g0.y, g0.z, g0.w, g1.x, g1.y, g1.z, g1.w};
; #pragma unroll
;           for (int e = 0; e < 4; ++e) { const unsigned w = pkbf(bflo(sw[c][e]) * rstd * gg[2 * e], bfhi(sw[c][e]) * rstd * gg[2 * e + 1]);
;               vn[(8 * c + 2 * e) * VN_STRIDE + srow] = (bf16)(w & 0xffffu); vn[(8 * c + 2 * e + 1) * VN_STRIDE + srow] = (bf16)(w >> 16); } }
	v_add_f32_e32 v116, v198, v199
	v_add_f32_e32 v115, v116, v115
	v_add_f32_e32 v104, v104, v115
	v_add_f32_e32 v104, v105, v104
	v_add_f32_e32 v104, v106, v104
	v_add_f32_e32 v104, v107, v104
	v_add_f32_e32 v104, v108, v104
	v_add_f32_e32 v104, v109, v104
	global_load_dwordx4 v[106:109], v2, s[12:13] offset:112
	global_load_dwordx4 v[116:119], v2, s[12:13] offset:96
	v_add_f32_e32 v104, v110, v104
	v_add_f32_e32 v104, v111, v104
	v_fmamk_f32 v104, v104, 0x3c800000, v205
	v_mul_f32_e32 v105, 0x4f800000, v104
	v_cmp_gt_f32_e32 vcc, s97, v104
	v_lshlrev_b32_e32 v3, 1, v3
	v_readlane_b32 s14, v247, 27
	v_cndmask_b32_e32 v104, v104, v105, vcc
	v_sqrt_f32_e32 v105, v104
	v_add3_u32 v3, s14, v77, v3
	global_load_dwordx4 v[120:123], v2, s[12:13] offset:176
	global_load_dwordx4 v[124:127], v2, s[12:13] offset:160
	global_load_dwordx4 v[128:131], v2, s[12:13] offset:144
	global_load_dwordx4 v[132:135], v2, s[12:13] offset:128
	v_lshlrev_b32_e32 v76, 3, v176
	v_add_u32_e32 v77, -1, v105
	v_fma_f32 v110, -v77, v105, v104
	v_cmp_ge_f32_e64 s[2:3], 0, v110
	v_add_u32_e32 v110, 1, v105
	s_nop 0
	v_cndmask_b32_e64 v77, v105, v77, s[2:3]
	v_fma_f32 v105, -v110, v105, v104
	v_cmp_lt_f32_e64 s[2:3], 0, v105
	s_nop 1
	v_cndmask_b32_e64 v77, v77, v110, s[2:3]
	v_mul_f32_e32 v105, 0x37800000, v77
	v_cndmask_b32_e32 v77, v77, v105, vcc
	v_cmp_class_f32_e32 vcc, v104, v206
	s_nop 1
	v_cndmask_b32_e32 v77, v77, v104, vcc
	v_div_scale_f32 v104, s[2:3], v77, v77, 1.0
	v_rcp_f32_e32 v105, v104
	s_and_b32 s2, s17, 64
	v_readlane_b32 s3, v248, 1
	s_or_b32 s2, s3, s2
	v_fma_f32 v110, -v104, v105, 1.0
	v_fmac_f32_e32 v105, v110, v105
	v_div_scale_f32 v110, vcc, 1.0, v77, 1.0
	v_mul_f32_e32 v111, v110, v105
	v_fma_f32 v115, -v104, v111, v110
	v_fmac_f32_e32 v111, v115, v105
	v_fma_f32 v104, -v104, v111, v110
	v_div_fmas_f32 v104, v104, v105, v111
	v_div_fixup_f32 v104, v104, v77, 1.0
	v_pk_mul_f32 v[110:111], v[104:105], v[136:137] op_sel_hi:[0,1]
	s_waitcnt vmcnt(8)
	v_pk_mul_f32 v[72:73], v[110:111], v[72:73]
	v_pk_mul_f32 v[48:49], v[104:105], v[48:49] op_sel_hi:[0,1]
	v_cvt_pk_bf16_f32 v72, v72, v73
	ds_write_b16 v3, v72
	ds_write_b16_d16_hi v3, v72 offset:272
	v_pk_mul_f32 v[72:73], v[104:105], v[138:139] op_sel_hi:[0,1]
	v_pk_mul_f32 v[72:73], v[72:73], v[74:75]
	s_waitcnt vmcnt(7)
	v_pk_mul_f32 v[48:49], v[48:49], v[54:55]
	v_cvt_pk_bf16_f32 v72, v72, v73
	ds_write_b16 v3, v72 offset:544
	ds_write_b16_d16_hi v3, v72 offset:816
	v_pk_mul_f32 v[72:73], v[104:105], v[140:141] op_sel_hi:[0,1]
	v_pk_mul_f32 v[68:69], v[72:73], v[68:69]
	v_cvt_pk_bf16_f32 v48, v48, v49
	v_cvt_pk_bf16_f32 v68, v68, v69
	ds_write_b16 v3, v68 offset:1088
	ds_write_b16_d16_hi v3, v68 offset:1360
	v_pk_mul_f32 v[68:69], v[104:105], v[142:143] op_sel_hi:[0,1]
	v_pk_mul_f32 v[68:69], v[68:69], v[70:71]
	v_pk_mul_f32 v[44:45], v[104:105], v[44:45] op_sel_hi:[0,1]
	v_cvt_pk_bf16_f32 v68, v68, v69
	ds_write_b16 v3, v68 offset:1632
	ds_write_b16_d16_hi v3, v68 offset:1904
	v_pk_mul_f32 v[68:69], v[104:105], v[144:145] op_sel_hi:[0,1]
	v_pk_mul_f32 v[64:65], v[68:69], v[64:65]
	v_pk_mul_f32 v[8:9], v[104:105], v[8:9] op_sel_hi:[0,1]
	v_cvt_pk_bf16_f32 v64, v64, v65
	ds_write_b16 v3, v64 offset:2176
	ds_write_b16_d16_hi v3, v64 offset:2448
	v_pk_mul_f32 v[64:65], v[104:105], v[146:147] op_sel_hi:[0,1]
	v_pk_mul_f32 v[64:65], v[64:65], v[66:67]
	v_pk_mul_f32 v[4:5], v[104:105], v[4:5] op_sel_hi:[0,1]
	v_cvt_pk_bf16_f32 v64, v64, v65
	ds_write_b16 v3, v64 offset:2720
	ds_write_b16_d16_hi v3, v64 offset:2992
	v_pk_mul_f32 v[64:65], v[104:105], v[148:149] op_sel_hi:[0,1]
	v_pk_mul_f32 v[60:61], v[64:65], v[60:61]
	v_mov_b32_e32 v77, v2
	v_cvt_pk_bf16_f32 v60, v60, v61
	ds_write_b16 v3, v60 offset:3264
	ds_write_b16_d16_hi v3, v60 offset:3536
	v_pk_mul_f32 v[60:61], v[104:105], v[150:151] op_sel_hi:[0,1]
	v_pk_mul_f32 v[60:61], v[60:61], v[62:63]
	s_waitcnt vmcnt(5)
	v_pk_mul_f32 v[44:45], v[44:45], v[108:109]
	v_cvt_pk_bf16_f32 v60, v60, v61
	ds_write_b16 v3, v60 offset:3808
	ds_write_b16_d16_hi v3, v60 offset:4080
	v_pk_mul_f32 v[60:61], v[104:105], v[152:153] op_sel_hi:[0,1]
	v_pk_mul_f32 v[56:57], v[60:61], v[56:57]
	v_cvt_pk_bf16_f32 v44, v44, v45
	v_cvt_pk_bf16_f32 v56, v56, v57
	ds_write_b16 v3, v56 offset:4352
	ds_write_b16_d16_hi v3, v56 offset:4624
	global_load_dwordx4 v[60:63], v2, s[12:13] offset:208
	global_load_dwordx4 v[64:67], v2, s[12:13] offset:192
	v_pk_mul_f32 v[56:57], v[104:105], v[154:155] op_sel_hi:[0,1]
	v_pk_mul_f32 v[56:57], v[56:57], v[58:59]
	s_waitcnt vmcnt(2)
; __device__ __forceinline__ unsigned pkbf(float lo, float hi) { typedef float f2_t __attribute__((ext_vector_type(2))); typedef __bf16 b2_t __attribute__((ext_vector_type(2))); f2_t v = {lo, hi}; b2_t b = __builtin_convertvector(v, b2_t); return __builtin_bit_cast(unsigned, b); }
; __device__ __forceinline__ float bflo(unsigned w) { return __uint_as_float(w << 16); }
; __device__ __forceinline__ float bfhi(unsigned w) { return __uint_as_float(w & 0xffff0000u); }
; __device__ __forceinline__ void mixer_phase256(const Args& A, int l, int vc, const bf16* Z, bf16* MIX, ss_t* ssa, ss_t* ssb, unsigned char* lds, int tid, int wid, int lane) {
;     ...
;       for (int c = 0; c < 8; ++c) { const f32x4 g0 = *(const f32x4*)(gs + 8 * c), g1 = *(const f32x4*)(gs + 8 * c + 4); const float gg[8] = {g0.x, g0.y, g0.z, g0.w, g1.x, g1.y, g1.z, g1.w};
; #pragma unroll
;           for (int e = 0; e < 4; ++e) { const unsigned w = pkbf(bflo(sw[c][e]) * rstd * gg[2 * e], bfhi(sw[c][e]) * rstd * gg[2 * e + 1]);
;               vn[(8 * c + 2 * e) * VN_STRIDE + srow] = (bf16)(w & 0xffffu); vn[(8 * c + 2 * e + 1) * VN_STRIDE + srow] = (bf16)(w >> 16); } }
;     }
;     asm volatile("" ::: "memory");
;     u32x4 q0[2]; attn_load_q(q0, Z, n, kvh, wid, lane);
	v_pk_mul_f32 v[8:9], v[8:9], v[134:135]
	v_cvt_pk_bf16_f32 v56, v56, v57
	ds_write_b16 v3, v56 offset:4896
	ds_write_b16_d16_hi v3, v56 offset:5168
	v_pk_mul_f32 v[56:57], v[104:105], v[92:93] op_sel_hi:[0,1]
	v_pk_mul_f32 v[52:53], v[56:57], v[52:53]
	v_cvt_pk_bf16_f32 v8, v8, v9
	v_cvt_pk_bf16_f32 v52, v52, v53
	ds_write_b16 v3, v52 offset:5440
	ds_write_b16_d16_hi v3, v52 offset:5712
	ds_write_b16 v3, v48 offset:5984
	ds_write_b16_d16_hi v3, v48 offset:6256
	v_pk_mul_f32 v[48:49], v[104:105], v[96:97] op_sel_hi:[0,1]
	v_pk_mul_f32 v[48:49], v[48:49], v[116:117]
	v_pk_mul_f32 v[4:5], v[4:5], v[126:127]
	v_cvt_pk_bf16_f32 v48, v48, v49
	ds_write_b16 v3, v48 offset:6528
	ds_write_b16_d16_hi v3, v48 offset:6800
	v_pk_mul_f32 v[48:49], v[104:105], v[94:95] op_sel_hi:[0,1]
	v_pk_mul_f32 v[48:49], v[48:49], v[118:119]
	v_cvt_pk_bf16_f32 v4, v4, v5
	v_cvt_pk_bf16_f32 v48, v48, v49
	ds_write_b16 v3, v48 offset:7072
	ds_write_b16_d16_hi v3, v48 offset:7344
	global_load_dwordx4 v[52:55], v2, s[12:13] offset:240
	global_load_dwordx4 v[56:59], v2, s[12:13] offset:224
	v_pk_mul_f32 v[48:49], v[104:105], v[50:51] op_sel_hi:[0,1]
	v_pk_mul_f32 v[48:49], v[48:49], v[106:107]
	s_nop 0
	v_cvt_pk_bf16_f32 v48, v48, v49
	ds_write_b16 v3, v48 offset:7616
	ds_write_b16_d16_hi v3, v48 offset:7888
	ds_write_b16 v3, v44 offset:8160
	ds_write_b16_d16_hi v3, v44 offset:8432
	v_pk_mul_f32 v[44:45], v[104:105], v[46:47] op_sel_hi:[0,1]
	v_pk_mul_f32 v[44:45], v[44:45], v[132:133]
	s_nop 0
	v_cvt_pk_bf16_f32 v44, v44, v45
	ds_write_b16 v3, v44 offset:8704
	ds_write_b16_d16_hi v3, v44 offset:8976
	ds_write_b16 v3, v8 offset:9248
	ds_write_b16_d16_hi v3, v8 offset:9520
	v_pk_mul_f32 v[8:9], v[104:105], v[98:99] op_sel_hi:[0,1]
	v_pk_mul_f32 v[8:9], v[8:9], v[128:129]
	v_mov_b32_e32 v45, v2
	v_cvt_pk_bf16_f32 v8, v8, v9
	ds_write_b16 v3, v8 offset:9792
	ds_write_b16_d16_hi v3, v8 offset:10064
	v_pk_mul_f32 v[8:9], v[104:105], v[10:11] op_sel_hi:[0,1]
	v_pk_mul_f32 v[8:9], v[8:9], v[130:131]
	s_nop 0
	v_cvt_pk_bf16_f32 v8, v8, v9
	ds_write_b16 v3, v8 offset:10336
	ds_write_b16_d16_hi v3, v8 offset:10608
	v_pk_mul_f32 v[8:9], v[104:105], v[100:101] op_sel_hi:[0,1]
	v_pk_mul_f32 v[8:9], v[8:9], v[124:125]
	s_nop 0
	v_cvt_pk_bf16_f32 v8, v8, v9
	ds_write_b16 v3, v8 offset:10880
	ds_write_b16_d16_hi v3, v8 offset:11152
	ds_write_b16 v3, v4 offset:11424
	ds_write_b16_d16_hi v3, v4 offset:11696
	v_pk_mul_f32 v[4:5], v[104:105], v[102:103] op_sel_hi:[0,1]
	v_pk_mul_f32 v[4:5], v[4:5], v[120:121]
	s_nop 0
	v_cvt_pk_bf16_f32 v4, v4, v5
	ds_write_b16 v3, v4 offset:11968
	ds_write_b16_d16_hi v3, v4 offset:12240
	v_pk_mul_f32 v[4:5], v[104:105], v[6:7] op_sel_hi:[0,1]
	v_pk_mul_f32 v[4:5], v[4:5], v[122:123]
	s_nop 0
	v_cvt_pk_bf16_f32 v4, v4, v5
	ds_write_b16 v3, v4 offset:12512
	ds_write_b16_d16_hi v3, v4 offset:12784
	v_mov_b32_e32 v4, v88
	v_mov_b32_e32 v5, v90
	v_pk_mul_f32 v[4:5], v[104:105], v[4:5] op_sel_hi:[0,1]
	v_mov_b32_e32 v90, v89
	s_waitcnt vmcnt(2)
	v_pk_mul_f32 v[4:5], v[4:5], v[64:65]
	s_nop 0
	v_cvt_pk_bf16_f32 v4, v4, v5
	ds_write_b16 v3, v4 offset:13056
	ds_write_b16_d16_hi v3, v4 offset:13328
	v_pk_mul_f32 v[4:5], v[104:105], v[90:91] op_sel_hi:[0,1]
	v_pk_mul_f32 v[4:5], v[4:5], v[66:67]
	s_nop 0
	v_cvt_pk_bf16_f32 v4, v4, v5
	ds_write_b16 v3, v4 offset:13600
	ds_write_b16_d16_hi v3, v4 offset:13872
	v_mov_b32_e32 v4, v84
	v_mov_b32_e32 v5, v86
	v_pk_mul_f32 v[4:5], v[104:105], v[4:5] op_sel_hi:[0,1]
	v_pk_mul_f32 v[4:5], v[4:5], v[60:61]
	v_mov_b32_e32 v86, v85
	v_cvt_pk_bf16_f32 v4, v4, v5
	ds_write_b16 v3, v4 offset:14144
	ds_write_b16_d16_hi v3, v4 offset:14416
	v_pk_mul_f32 v[4:5], v[104:105], v[86:87] op_sel_hi:[0,1]
	v_pk_mul_f32 v[4:5], v[4:5], v[62:63]
	s_nop 0
	v_cvt_pk_bf16_f32 v4, v4, v5
	ds_write_b16 v3, v4 offset:14688
	ds_write_b16_d16_hi v3, v4 offset:14960
	v_mov_b32_e32 v4, v80
	v_mov_b32_e32 v5, v82
	v_pk_mul_f32 v[4:5], v[104:105], v[4:5] op_sel_hi:[0,1]
	s_waitcnt vmcnt(0)
	v_pk_mul_f32 v[4:5], v[4:5], v[56:57]
	v_mov_b32_e32 v82, v81
	v_cvt_pk_bf16_f32 v4, v4, v5
	ds_write_b16 v3, v4 offset:15232
	ds_write_b16_d16_hi v3, v4 offset:15504
	v_pk_mul_f32 v[4:5], v[104:105], v[82:83] op_sel_hi:[0,1]
	v_pk_mul_f32 v[4:5], v[4:5], v[58:59]
	s_nop 0
	v_cvt_pk_bf16_f32 v4, v4, v5
	ds_write_b16 v3, v4 offset:15776
	ds_write_b16_d16_hi v3, v4 offset:16048
	v_mov_b32_e32 v4, v0
	v_mov_b32_e32 v5, v78
	v_pk_mul_f32 v[4:5], v[104:105], v[4:5] op_sel_hi:[0,1]
	v_pk_mul_f32 v[4:5], v[4:5], v[52:53]
	v_mov_b32_e32 v78, v1
	v_cvt_pk_bf16_f32 v0, v4, v5
	ds_write_b16 v3, v0 offset:16320
	ds_write_b16_d16_hi v3, v0 offset:16592
	v_pk_mul_f32 v[0:1], v[104:105], v[78:79] op_sel_hi:[0,1]
	v_pk_mul_f32 v[0:1], v[0:1], v[54:55]
	s_nop 0
	v_cvt_pk_bf16_f32 v0, v0, v1
	ds_write_b16 v3, v0 offset:16864
	ds_write_b16_d16_hi v3, v0 offset:17136
	v_or_b32_e32 v3, s2, v175
	v_mov_b64_e32 v[0:1], s[82:83]
	v_mad_i64_i32 v[0:1], s[2:3], v3, s85, v[0:1]
	s_lshl_b32 s2, s73, 5
	s_andn2_b32 s2, s2, 63
	v_readlane_b32 s3, v248, 0
	s_add_i32 s2, s2, s3
	v_lshrrev_b32_e32 v3, 1, v113
	s_ashr_i32 s3, s2, 31
	v_and_b32_e32 v3, 24, v3
	v_lshl_add_u64 v[0:1], s[2:3], 1, v[0:1]
	v_lshlrev_b32_e32 v44, 1, v3
	v_lshl_add_u64 v[0:1], v[0:1], 0, v[44:45]
	s_mov_b64 s[2:3], 0x1000
	v_lshl_add_u64 v[8:9], v[0:1], 0, s[2:3]
	s_movk_i32 s2, 0x1000
	v_mov_b32_e32 v200, s73
	v_and_b32_e32 v201, 1, v200
	v_lshrrev_b32_e32 v200, 1, v200
	v_readlane_b32 s100, v249, 63
	v_and_b32_e32 v203, 15, v174
	v_lshl_add_u32 v203, v201, 6, v203
	v_add_u32_e32 v202, s100, v200
	v_readlane_b32 s100, v248, 1
	v_lshrrev_b32_e32 v200, 4, v174
	v_mov_b32_e32 v201, s78
	v_add_u32_e32 v203, s100, v203
; __device__ __forceinline__ unsigned pkbf(float lo, float hi) { typedef float f2_t __attribute__((ext_vector_type(2))); typedef __bf16 b2_t __attribute__((ext_vector_type(2))); f2_t v = {lo, hi}; b2_t b = __builtin_convertvector(v, b2_t); return __builtin_bit_cast(unsigned, b); }
; __device__ __forceinline__ void mixer_phase256(const Args& A, int l, int vc, const bf16* Z, bf16* MIX, ss_t* ssa, ss_t* ssb, unsigned char* lds, int tid, int wid, int lane) {
;     ...
;     u32x4 q0[2]; attn_load_q(q0, Z, n, kvh, wid, lane);
;     u32x2 uw[4][4];
; #pragma unroll
;     for (int j = 0; j < 4; ++j)
; #pragma unroll
;         for (int dt = 0; dt < 4; ++dt) uw[j][dt] = *(const u32x2*)(Z + (size_t)((cb + j) * 128 + st) * INW + h * 64 + 16 * dt + 4 * fq);
;     __syncthreads();
;     {
;         bf16x8 bfr[4];
; #pragma unroll
;         for (int ks = 0; ks < 4; ++ks) { float f[8] = {wa[ks][0].x, wa[ks][0].y, wa[ks][0].z, wa[ks][0].w, wa[ks][1].x, wa[ks][1].y, wa[ks][1].z, wa[ks][1].w}; const int s0 = 32 * ks + 8 * fq;
; #pragma unroll
;             for (int e = 0; e < 8; ++e) f[e] = (s0 + e <= st) ? f[e] : 0.f;
;             u32x4 w; w.x = pkbf(f[0], f[1]); w.y = pkbf(f[2], f[3]); w.z = pkbf(f[4], f[5]); w.w = pkbf(f[6], f[7]); bfr[ks] = __builtin_bit_cast(bf16x8, w); }
	v_mul_u32_u24_e32 v251, 0x1c00, v203
	v_lshl_add_u32 v251, v202, 7, v251
	v_lshl_add_u32 v251, v200, 4, v251
	v_add_u32_e32 v251, 0x18201000, v251
	v_readlane_b32 s100, v250, 28
	v_readlane_b32 s101, v250, 29
	s_nop 4
	global_load_dwordx4 v[116:119], v251, s[100:101]
	global_load_dwordx4 v[120:123], v251, s[100:101] offset:64
	v_add_u32_e32 v251, 0x1c000, v251
	global_load_dwordx4 v[124:127], v251, s[100:101]
	global_load_dwordx4 v[128:131], v251, s[100:101] offset:64
	v_add_u32_e32 v251, 0x1c000, v251
	global_load_dwordx4 v[132:135], v251, s[100:101]
	global_load_dwordx4 v[136:139], v251, s[100:101] offset:64
	v_add_u32_e32 v251, 0x1c000, v251
	global_load_dwordx4 v[140:143], v251, s[100:101]
	global_load_dwordx4 v[144:147], v251, s[100:101] offset:64
	v_readlane_b32 s100, v250, 26
	v_readlane_b32 s101, v250, 27
	v_lshlrev_b32_e32 v203, 5, v200
	v_lshl_add_u32 v203, v201, 8, v203
	s_nop 2
	global_load_dwordx4 v[148:151], v203, s[100:101]
	global_load_dwordx4 v[152:155], v203, s[100:101] offset:16
	global_load_dwordx4 v[156:159], v203, s[100:101] offset:128
	global_load_dwordx4 v[180:183], v203, s[100:101] offset:144
	v_readlane_b32 s100, v250, 32
	v_readlane_b32 s101, v250, 33
	v_lshl_add_u32 v203, v201, 4, v202
	v_lshlrev_b32_e32 v203, 2, v203
	s_nop 2
	global_load_dword v184, v203, s[100:101]
	v_add_co_u32_e32 v0, vcc, s2, v0
	v_readlane_b32 s2, v248, 4
	s_nop 0
	v_addc_co_u32_e32 v1, vcc, 0, v1, vcc
	v_readlane_b32 s3, v248, 5
	s_nop 0
	s_nop 0
	s_nop 0
	v_lshl_add_u64 v[0:1], s[2:3], 0, v[76:77]
	v_readlane_b32 s2, v248, 9
	v_cmp_le_i32_e32 vcc, v76, v114
	v_or_b32_e32 v3, 2, v76
	v_add_u32_e32 v78, s2, v114
	v_mad_i64_i32 v[46:47], s[2:3], v78, s85, v[0:1]
	v_readlane_b32 s2, v248, 7
	global_load_dwordx2 v[86:87], v[46:47], off
	global_load_dwordx2 v[84:85], v[46:47], off offset:32
	global_load_dwordx2 v[82:83], v[46:47], off offset:64
	global_load_dwordx2 v[80:81], v[46:47], off offset:96
	v_add_u32_e32 v66, s2, v114
	v_mad_i64_i32 v[46:47], s[2:3], v66, s85, v[0:1]
	v_readlane_b32 s2, v248, 8
	global_load_dwordx2 v[74:75], v[46:47], off
	global_load_dwordx2 v[72:73], v[46:47], off offset:32
	global_load_dwordx2 v[70:71], v[46:47], off offset:64
	global_load_dwordx2 v[68:69], v[46:47], off offset:96
	v_add_u32_e32 v56, s2, v114
	v_mad_i64_i32 v[46:47], s[2:3], v56, s85, v[0:1]
	v_readlane_b32 s2, v248, 10
	global_load_dwordx2 v[64:65], v[46:47], off
	global_load_dwordx2 v[62:63], v[46:47], off offset:32
	global_load_dwordx2 v[60:61], v[46:47], off offset:64
	global_load_dwordx2 v[58:59], v[46:47], off offset:96
	v_add_u32_e32 v46, s2, v114
	v_mad_i64_i32 v[0:1], s[2:3], v46, s85, v[0:1]
	global_load_dwordx2 v[54:55], v[0:1], off
	global_load_dwordx2 v[52:53], v[0:1], off offset:32
	global_load_dwordx2 v[50:51], v[0:1], off offset:64
	global_load_dwordx2 v[48:49], v[0:1], off offset:96
	v_and_b32_e32 v96, 15, v174
	v_lshrrev_b32_e32 v97, 4, v174
	s_lshl_b32 s20, s73, 4
	v_add_u32_e32 v98, s20, v96
	v_lshlrev_b32_e32 v99, 3, v97
	v_sub_u32_e32 v99, v98, v99
	v_mov_b32_e32 v3, v99
	v_cmp_le_i32_e64 s[4:5], 0, v3
	v_cmp_le_i32_e64 s[6:7], 1, v3
	v_cmp_le_i32_e64 s[8:9], 2, v3
	v_cmp_le_i32_e64 s[10:11], 3, v3
	v_cmp_le_i32_e64 s[12:13], 4, v3
	v_cmp_le_i32_e64 s[14:15], 5, v3
	v_cmp_le_i32_e64 s[16:17], 6, v3
	v_cmp_le_i32_e64 s[18:19], 7, v3
	v_cndmask_b32_e64 v40, 0, v40, s[4:5]
	v_cndmask_b32_e64 v41, 0, v41, s[6:7]
	v_cndmask_b32_e64 v42, 0, v42, s[8:9]
	v_cndmask_b32_e64 v43, 0, v43, s[10:11]
	v_cndmask_b32_e64 v36, 0, v36, s[12:13]
	v_cndmask_b32_e64 v37, 0, v37, s[14:15]
	v_cndmask_b32_e64 v38, 0, v38, s[16:17]
	v_cndmask_b32_e64 v39, 0, v39, s[18:19]
	v_cvt_pk_bf16_f32 v4, v40, v41
	v_cvt_pk_bf16_f32 v5, v42, v43
	v_cvt_pk_bf16_f32 v6, v36, v37
	v_cvt_pk_bf16_f32 v7, v38, v39
	v_add_u32_e32 v3, 0xffffffe0, v99
	v_cmp_le_i32_e64 s[4:5], 0, v3
	v_cmp_le_i32_e64 s[6:7], 1, v3
	v_cmp_le_i32_e64 s[8:9], 2, v3
	v_cmp_le_i32_e64 s[10:11], 3, v3
	v_cmp_le_i32_e64 s[12:13], 4, v3
	v_cmp_le_i32_e64 s[14:15], 5, v3
	v_cmp_le_i32_e64 s[16:17], 6, v3
	v_cmp_le_i32_e64 s[18:19], 7, v3
	v_cndmask_b32_e64 v16, 0, v16, s[4:5]
	v_cndmask_b32_e64 v17, 0, v17, s[6:7]
	v_cndmask_b32_e64 v18, 0, v18, s[8:9]
	v_cndmask_b32_e64 v19, 0, v19, s[10:11]
	v_cndmask_b32_e64 v32, 0, v32, s[12:13]
	v_cndmask_b32_e64 v33, 0, v33, s[14:15]
	v_cndmask_b32_e64 v34, 0, v34, s[16:17]
	v_cndmask_b32_e64 v35, 0, v35, s[18:19]
	v_cvt_pk_bf16_f32 v8, v16, v17
	v_cvt_pk_bf16_f32 v9, v18, v19
	v_cvt_pk_bf16_f32 v10, v32, v33
	v_cvt_pk_bf16_f32 v11, v34, v35
	v_add_u32_e32 v3, 0xffffffc0, v99
	v_cmp_le_i32_e64 s[4:5], 0, v3
	v_cmp_le_i32_e64 s[6:7], 1, v3
	v_cmp_le_i32_e64 s[8:9], 2, v3
	v_cmp_le_i32_e64 s[10:11], 3, v3
	v_cmp_le_i32_e64 s[12:13], 4, v3
	v_cmp_le_i32_e64 s[14:15], 5, v3
	v_cmp_le_i32_e64 s[16:17], 6, v3
	v_cmp_le_i32_e64 s[18:19], 7, v3
	v_cndmask_b32_e64 v28, 0, v28, s[4:5]
	v_cndmask_b32_e64 v29, 0, v29, s[6:7]
	v_cndmask_b32_e64 v30, 0, v30, s[8:9]
	v_cndmask_b32_e64 v31, 0, v31, s[10:11]
	v_cndmask_b32_e64 v24, 0, v24, s[12:13]
	v_cndmask_b32_e64 v25, 0, v25, s[14:15]
	v_cndmask_b32_e64 v26, 0, v26, s[16:17]
	v_cndmask_b32_e64 v27, 0, v27, s[18:19]
	v_cvt_pk_bf16_f32 v88, v28, v29
	v_cvt_pk_bf16_f32 v89, v30, v31
	v_cvt_pk_bf16_f32 v90, v24, v25
	v_cvt_pk_bf16_f32 v91, v26, v27
	v_add_u32_e32 v3, 0xffffffa0, v99
	v_cmp_le_i32_e64 s[4:5], 0, v3
	v_cmp_le_i32_e64 s[6:7], 1, v3
	v_cmp_le_i32_e64 s[8:9], 2, v3
	v_cmp_le_i32_e64 s[10:11], 3, v3
	v_cmp_le_i32_e64 s[12:13], 4, v3
	v_cmp_le_i32_e64 s[14:15], 5, v3
	v_cmp_le_i32_e64 s[16:17], 6, v3
	v_cmp_le_i32_e64 s[18:19], 7, v3
	v_cndmask_b32_e64 v12, 0, v12, s[4:5]
	v_cndmask_b32_e64 v13, 0, v13, s[6:7]
	v_cndmask_b32_e64 v14, 0, v14, s[8:9]
	v_cndmask_b32_e64 v15, 0, v15, s[10:11]
	v_cndmask_b32_e64 v20, 0, v20, s[12:13]
	v_cndmask_b32_e64 v21, 0, v21, s[14:15]
	v_cndmask_b32_e64 v22, 0, v22, s[16:17]
	v_cndmask_b32_e64 v23, 0, v23, s[18:19]
	v_cvt_pk_bf16_f32 v92, v12, v13
	v_cvt_pk_bf16_f32 v93, v14, v15
	v_cvt_pk_bf16_f32 v94, v20, v21
	v_cvt_pk_bf16_f32 v95, v22, v23
	s_waitcnt lgkmcnt(0)
	s_barrier
; __device__ __forceinline__ void ss_add(ss_t* p, float sq) { const float fl = floorf(sq); const unsigned hi = (unsigned)fl, lo = (unsigned)((sq - fl) * 4294967296.0f); atomicAdd(p, ((ss_t)hi << 32) | (ss_t)lo); }
; __device__ __forceinline__ unsigned pkbf(float lo, float hi) { typedef float f2_t __attribute__((ext_vector_type(2))); typedef __bf16 b2_t __attribute__((ext_vector_type(2))); f2_t v = {lo, hi}; b2_t b = __builtin_convertvector(v, b2_t); return __builtin_bit_cast(unsigned, b); }
; __device__ __forceinline__ float bflo(unsigned w) { return __uint_as_float(w << 16); }
; __device__ __forceinline__ float bfhi(unsigned w) { return __uint_as_float(w & 0xffff0000u); }
; #define MFMA16(a, b, c) __builtin_amdgcn_mfma_f32_16x16x32_bf16((a), (b), (c), 0, 0, 0)
; __device__ __forceinline__ void mixer_phase256(const Args& A, int l, int vc, const bf16* Z, bf16* MIX, ss_t* ssa, ss_t* ssb, unsigned char* lds, int tid, int wid, int lane) {
;     ...
; #pragma unroll
;         for (int j = 0; j < 4; ++j) {
;             const bf16* vn = VN + j * 64 * VN_STRIDE; const size_t tok = (size_t)((cb + j) * 128 + st); float sq = 0.f;
; #pragma unroll
;             for (int dt = 0; dt < 4; ++dt) {
;                 f32x4 acc = (f32x4){0.f, 0.f, 0.f, 0.f};
; #pragma unroll
;                 for (int ks = 0; ks < 4; ++ks) if (ks < nks) { const bf16x8 a = *(const bf16x8*)(vn + (16 * dt + fr) * VN_STRIDE + 32 * ks + 8 * fq); acc = MFMA16(a, bfr[ks], acc); }
;                 const float v0 = bflo(uw[j][dt].x) * (acc[0] + sbias), v1 = bfhi(uw[j][dt].x) * (acc[1] + sbias), v2 = bflo(uw[j][dt].y) * (acc[2] + sbias), v3 = bfhi(uw[j][dt].y) * (acc[3] + sbias);
;                 sq += (v0 * v0 + v1 * v1) + (v2 * v2 + v3 * v3);
;                 u32x2 w; w.x = pkbf(v0, v1); w.y = pkbf(v2, v3);
;                 *(u32x2*)(MIX + tok * DM + h * 64 + 16 * dt + 4 * fq) = w;
;             }
;             sq += __shfl_xor(sq, 16); sq += __shfl_xor(sq, 32); if (fq == 0) ss_add(ssa + tok, sq);
	v_readlane_b32 s100, v250, 28
	v_readlane_b32 s101, v250, 29
	v_readlane_b32 s21, v248, 6
	v_readlane_b32 s22, v248, 3
	s_lshr_b32 s23, s73, 1
	v_mul_u32_u24_e32 v100, 0x110, v96
	v_lshl_add_u32 v100, v97, 4, v100
	v_add_u32_e32 v100, 0x11c00, v100
	v_xor_b32_e32 v56, 16, v174
	v_lshlrev_b32_e32 v56, 2, v56
	v_xor_b32_e32 v57, 32, v174
	v_lshlrev_b32_e32 v57, 2, v57
	v_cmp_eq_u32_e64 s[24:25], 0, v97
	s_lshl_b32 s26, s21, 7
	v_add_u32_e32 v3, s26, v98
	v_lshlrev_b32_e32 v253, 12, v3
	s_lshl_b32 s26, s22, 7
	s_add_i32 s26, s26, 0x1ba00000
	v_add_u32_e32 v253, s26, v253
	v_lshl_add_u32 v253, v97, 3, v253
	s_add_i32 s26, s78, 9
	s_lshl_b32 s26, s26, 16
	v_lshl_add_u32 v254, v3, 3, s26
	ds_read_b128 v[12:15], v100 offset:0
	ds_read_b128 v[28:31], v100 offset:4352
	s_cmp_lt_u32 s23, 1
	s_cbranch_scc1 .Lsg2_r_0
	ds_read_b128 v[16:19], v100 offset:64
	ds_read_b128 v[32:35], v100 offset:4416
	s_cmp_lt_u32 s23, 2
	s_cbranch_scc1 .Lsg2_r_0
	ds_read_b128 v[20:23], v100 offset:128
	ds_read_b128 v[36:39], v100 offset:4480
	s_cmp_lt_u32 s23, 3
	s_cbranch_scc1 .Lsg2_r_0
	ds_read_b128 v[24:27], v100 offset:192
	ds_read_b128 v[40:43], v100 offset:4544
.Lsg2_r_0:
	s_waitcnt lgkmcnt(0)
	ds_read_b128 v[212:215], v100 offset:8704
	ds_read_b128 v[228:231], v100 offset:13056
	s_cmp_lt_u32 s23, 1
	s_cbranch_scc1 .Lsg2_r_1
	ds_read_b128 v[216:219], v100 offset:8768
	ds_read_b128 v[232:235], v100 offset:13120
	s_cmp_lt_u32 s23, 2
	s_cbranch_scc1 .Lsg2_r_1
	ds_read_b128 v[220:223], v100 offset:8832
	ds_read_b128 v[236:239], v100 offset:13184
	s_cmp_lt_u32 s23, 3
	s_cbranch_scc1 .Lsg2_r_1
	ds_read_b128 v[224:227], v100 offset:8896
	ds_read_b128 v[240:243], v100 offset:13248
.Lsg2_r_1:
	v_mfma_f32_16x16x32_bf16 v[186:189], v[12:15], v[4:7], 0
	v_mfma_f32_16x16x32_bf16 v[190:193], v[28:31], v[4:7], 0
	s_cmp_lt_u32 s23, 1
	s_cbranch_scc1 .Lsg2_m_0
	v_mfma_f32_16x16x32_bf16 v[186:189], v[16:19], v[8:11], v[186:189]
	v_mfma_f32_16x16x32_bf16 v[190:193], v[32:35], v[8:11], v[190:193]
	s_cmp_lt_u32 s23, 2
	s_cbranch_scc1 .Lsg2_m_0
	v_mfma_f32_16x16x32_bf16 v[186:189], v[20:23], v[88:91], v[186:189]
	v_mfma_f32_16x16x32_bf16 v[190:193], v[36:39], v[88:91], v[190:193]
	s_cmp_lt_u32 s23, 3
	s_cbranch_scc1 .Lsg2_m_0
	v_mfma_f32_16x16x32_bf16 v[186:189], v[24:27], v[92:95], v[186:189]
	v_mfma_f32_16x16x32_bf16 v[190:193], v[40:43], v[92:95], v[190:193]
.Lsg2_m_0:
	s_waitcnt lgkmcnt(0)
	ds_read_b128 v[12:15], v100 offset:17408
	ds_read_b128 v[28:31], v100 offset:21760
	s_cmp_lt_u32 s23, 1
	s_cbranch_scc1 .Lsg2_r_2
	ds_read_b128 v[16:19], v100 offset:17472
	ds_read_b128 v[32:35], v100 offset:21824
	s_cmp_lt_u32 s23, 2
	s_cbranch_scc1 .Lsg2_r_2
	ds_read_b128 v[20:23], v100 offset:17536
	ds_read_b128 v[36:39], v100 offset:21888
	s_cmp_lt_u32 s23, 3
	s_cbranch_scc1 .Lsg2_r_2
	ds_read_b128 v[24:27], v100 offset:17600
	ds_read_b128 v[40:43], v100 offset:21952
.Lsg2_r_2:
	v_mfma_f32_16x16x32_bf16 v[194:197], v[212:215], v[4:7], 0
	v_mfma_f32_16x16x32_bf16 v[198:201], v[228:231], v[4:7], 0
	s_cmp_lt_u32 s23, 1
	s_cbranch_scc1 .Lsg2_m_1
	v_mfma_f32_16x16x32_bf16 v[194:197], v[216:219], v[8:11], v[194:197]
	v_mfma_f32_16x16x32_bf16 v[198:201], v[232:235], v[8:11], v[198:201]
	s_cmp_lt_u32 s23, 2
	s_cbranch_scc1 .Lsg2_m_1
	v_mfma_f32_16x16x32_bf16 v[194:197], v[220:223], v[88:91], v[194:197]
	v_mfma_f32_16x16x32_bf16 v[198:201], v[236:239], v[88:91], v[198:201]
	s_cmp_lt_u32 s23, 3
	s_cbranch_scc1 .Lsg2_m_1
	v_mfma_f32_16x16x32_bf16 v[194:197], v[224:227], v[92:95], v[194:197]
	v_mfma_f32_16x16x32_bf16 v[198:201], v[240:243], v[92:95], v[198:201]
.Lsg2_m_1:
	s_waitcnt vmcnt(0)
	s_nop 3
	v_lshlrev_b32_e32 v96, 16, v86
	v_and_b32_e32 v97, 0xffff0000, v86
	v_lshlrev_b32_e32 v98, 16, v87
	v_and_b32_e32 v99, 0xffff0000, v87
	v_pk_add_f32 v[186:187], v[112:113], v[186:187] op_sel_hi:[0,1]
	v_pk_add_f32 v[188:189], v[112:113], v[188:189] op_sel_hi:[0,1]
	v_pk_mul_f32 v[186:187], v[96:97], v[186:187]
	v_pk_mul_f32 v[188:189], v[98:99], v[188:189]
	v_pk_mul_f32 v[202:203], v[186:187], v[186:187]
	v_pk_fma_f32 v[202:203], v[188:189], v[188:189], v[202:203]
	v_cvt_pk_bf16_f32 v0, v186, v187
	v_cvt_pk_bf16_f32 v1, v188, v189
	global_store_dwordx2 v253, v[0:1], s[100:101] offset:0
	v_lshlrev_b32_e32 v96, 16, v84
	v_and_b32_e32 v97, 0xffff0000, v84
	v_lshlrev_b32_e32 v98, 16, v85
	v_and_b32_e32 v99, 0xffff0000, v85
	v_pk_add_f32 v[190:191], v[112:113], v[190:191] op_sel_hi:[0,1]
	v_pk_add_f32 v[192:193], v[112:113], v[192:193] op_sel_hi:[0,1]
	v_pk_mul_f32 v[190:191], v[96:97], v[190:191]
	v_pk_mul_f32 v[192:193], v[98:99], v[192:193]
	v_pk_fma_f32 v[202:203], v[190:191], v[190:191], v[202:203]
	v_pk_fma_f32 v[202:203], v[192:193], v[192:193], v[202:203]
	v_cvt_pk_bf16_f32 v46, v190, v191
	v_cvt_pk_bf16_f32 v47, v192, v193
	global_store_dwordx2 v253, v[46:47], s[100:101] offset:32
	s_waitcnt lgkmcnt(0)
	ds_read_b128 v[212:215], v100 offset:26112
	ds_read_b128 v[228:231], v100 offset:30464
	s_cmp_lt_u32 s23, 1
	s_cbranch_scc1 .Lsg2_r_3
	ds_read_b128 v[216:219], v100 offset:26176
	ds_read_b128 v[232:235], v100 offset:30528
	s_cmp_lt_u32 s23, 2
	s_cbranch_scc1 .Lsg2_r_3
	ds_read_b128 v[220:223], v100 offset:26240
	ds_read_b128 v[236:239], v100 offset:30592
	s_cmp_lt_u32 s23, 3
	s_cbranch_scc1 .Lsg2_r_3
	ds_read_b128 v[224:227], v100 offset:26304
	ds_read_b128 v[240:243], v100 offset:30656

; __device__ __forceinline__ void ss_add(ss_t* p, float sq) { const float fl = floorf(sq); const unsigned hi = (unsigned)fl, lo = (unsigned)((sq - fl) * 4294967296.0f); atomicAdd(p, ((ss_t)hi << 32) | (ss_t)lo); }
; __device__ __forceinline__ unsigned pkbf(float lo, float hi) { typedef float f2_t __attribute__((ext_vector_type(2))); typedef __bf16 b2_t __attribute__((ext_vector_type(2))); f2_t v = {lo, hi}; b2_t b = __builtin_convertvector(v, b2_t); return __builtin_bit_cast(unsigned, b); }
; __device__ __forceinline__ float bflo(unsigned w) { return __uint_as_float(w << 16); }
; __device__ __forceinline__ float bfhi(unsigned w) { return __uint_as_float(w & 0xffff0000u); }
; __device__ __forceinline__ void mixer_phase256(const Args& A, int l, int vc, const bf16* Z, bf16* MIX, ss_t* ssa, ss_t* ssb, unsigned char* lds, int tid, int wid, int lane) {
;     ...
;                 const float v0 = bflo(uw[j][dt].x) * (acc[0] + sbias), v1 = bfhi(uw[j][dt].x) * (acc[1] + sbias), v2 = bflo(uw[j][dt].y) * (acc[2] + sbias), v3 = bfhi(uw[j][dt].y) * (acc[3] + sbias);
;                 sq += (v0 * v0 + v1 * v1) + (v2 * v2 + v3 * v3);
;                 u32x2 w; w.x = pkbf(v0, v1); w.y = pkbf(v2, v3);
;                 *(u32x2*)(MIX + tok * DM + h * 64 + 16 * dt + 4 * fq) = w;
;             }
;             sq += __shfl_xor(sq, 16); sq += __shfl_xor(sq, 32); if (fq == 0) ss_add(ssa + tok, sq);
.Lsg2_m_2:
	s_nop 3
	v_lshlrev_b32_e32 v96, 16, v82
	v_and_b32_e32 v97, 0xffff0000, v82
	v_lshlrev_b32_e32 v98, 16, v83
	v_and_b32_e32 v99, 0xffff0000, v83
	v_pk_add_f32 v[194:195], v[112:113], v[194:195] op_sel_hi:[0,1]
	v_pk_add_f32 v[196:197], v[112:113], v[196:197] op_sel_hi:[0,1]
	v_pk_mul_f32 v[194:195], v[96:97], v[194:195]
	v_pk_mul_f32 v[196:197], v[98:99], v[196:197]
	v_pk_fma_f32 v[202:203], v[194:195], v[194:195], v[202:203]
	v_pk_fma_f32 v[202:203], v[196:197], v[196:197], v[202:203]
	v_cvt_pk_bf16_f32 v0, v194, v195
	v_cvt_pk_bf16_f32 v1, v196, v197
	global_store_dwordx2 v253, v[0:1], s[100:101] offset:64
	v_lshlrev_b32_e32 v96, 16, v80
	v_and_b32_e32 v97, 0xffff0000, v80
	v_lshlrev_b32_e32 v98, 16, v81
	v_and_b32_e32 v99, 0xffff0000, v81
	v_pk_add_f32 v[198:199], v[112:113], v[198:199] op_sel_hi:[0,1]
	v_pk_add_f32 v[200:201], v[112:113], v[200:201] op_sel_hi:[0,1]
	v_pk_mul_f32 v[198:199], v[96:97], v[198:199]
	v_pk_mul_f32 v[200:201], v[98:99], v[200:201]
	v_pk_fma_f32 v[202:203], v[198:199], v[198:199], v[202:203]
	v_pk_fma_f32 v[202:203], v[200:201], v[200:201], v[202:203]
	v_cvt_pk_bf16_f32 v46, v198, v199
	v_cvt_pk_bf16_f32 v47, v200, v201
	global_store_dwordx2 v253, v[46:47], s[100:101] offset:96
	v_add_f32_e32 v3, v202, v203
	ds_bpermute_b32 v45, v56, v3
	s_waitcnt lgkmcnt(0)
	v_add_f32_e32 v3, v3, v45
	ds_bpermute_b32 v45, v57, v3
	s_waitcnt lgkmcnt(0)
	v_add_f32_e32 v3, v3, v45
	s_mov_b64 exec, s[24:25]
	v_floor_f32_e32 v45, v3
	v_sub_f32_e32 v3, v3, v45
	v_mul_f32_e32 v3, 0x4f800000, v3
	v_cvt_u32_f32_e32 v79, v45
	v_cvt_u32_f32_e32 v78, v3
	global_atomic_add_x2 v254, v[78:79], s[100:101] offset:0
	s_mov_b64 exec, -1
	v_add_u32_e32 v253, 0x80000, v253
	s_waitcnt lgkmcnt(0)
	ds_read_b128 v[12:15], v100 offset:34816
	ds_read_b128 v[28:31], v100 offset:39168
	s_cmp_lt_u32 s23, 1
	s_cbranch_scc1 .Lsg2_r_4
	ds_read_b128 v[16:19], v100 offset:34880
	ds_read_b128 v[32:35], v100 offset:39232
	s_cmp_lt_u32 s23, 2
	s_cbranch_scc1 .Lsg2_r_4
	ds_read_b128 v[20:23], v100 offset:34944
	ds_read_b128 v[36:39], v100 offset:39296
	s_cmp_lt_u32 s23, 3
	s_cbranch_scc1 .Lsg2_r_4
	ds_read_b128 v[24:27], v100 offset:35008
	ds_read_b128 v[40:43], v100 offset:39360

; __device__ __forceinline__ unsigned pkbf(float lo, float hi) { typedef float f2_t __attribute__((ext_vector_type(2))); typedef __bf16 b2_t __attribute__((ext_vector_type(2))); f2_t v = {lo, hi}; b2_t b = __builtin_convertvector(v, b2_t); return __builtin_bit_cast(unsigned, b); }
; __device__ __forceinline__ float bflo(unsigned w) { return __uint_as_float(w << 16); }
; __device__ __forceinline__ float bfhi(unsigned w) { return __uint_as_float(w & 0xffff0000u); }
; #define MFMA16(a, b, c) __builtin_amdgcn_mfma_f32_16x16x32_bf16((a), (b), (c), 0, 0, 0)
; __device__ __forceinline__ void mixer_phase256(const Args& A, int l, int vc, const bf16* Z, bf16* MIX, ss_t* ssa, ss_t* ssb, unsigned char* lds, int tid, int wid, int lane) {
;     ...
;         for (int j = 0; j < 4; ++j) {
;             const bf16* vn = VN + j * 64 * VN_STRIDE; const size_t tok = (size_t)((cb + j) * 128 + st); float sq = 0.f;
; #pragma unroll
;             for (int dt = 0; dt < 4; ++dt) {
;                 f32x4 acc = (f32x4){0.f, 0.f, 0.f, 0.f};
; #pragma unroll
;                 for (int ks = 0; ks < 4; ++ks) if (ks < nks) { const bf16x8 a = *(const bf16x8*)(vn + (16 * dt + fr) * VN_STRIDE + 32 * ks + 8 * fq); acc = MFMA16(a, bfr[ks], acc); }
;                 const float v0 = bflo(uw[j][dt].x) * (acc[0] + sbias), v1 = bfhi(uw[j][dt].x) * (acc[1] + sbias), v2 = bflo(uw[j][dt].y) * (acc[2] + sbias), v3 = bfhi(uw[j][dt].y) * (acc[3] + sbias);
;                 sq += (v0 * v0 + v1 * v1) + (v2 * v2 + v3 * v3);
;                 u32x2 w; w.x = pkbf(v0, v1); w.y = pkbf(v2, v3);
;                 *(u32x2*)(MIX + tok * DM + h * 64 + 16 * dt + 4 * fq) = w;
;             }
.Lsg2_m_3:
	s_nop 3
	v_lshlrev_b32_e32 v96, 16, v74
	v_and_b32_e32 v97, 0xffff0000, v74
	v_lshlrev_b32_e32 v98, 16, v75
	v_and_b32_e32 v99, 0xffff0000, v75
	v_pk_add_f32 v[186:187], v[112:113], v[186:187] op_sel_hi:[0,1]
	v_pk_add_f32 v[188:189], v[112:113], v[188:189] op_sel_hi:[0,1]
	v_pk_mul_f32 v[186:187], v[96:97], v[186:187]
	v_pk_mul_f32 v[188:189], v[98:99], v[188:189]
	v_pk_mul_f32 v[202:203], v[186:187], v[186:187]
	v_pk_fma_f32 v[202:203], v[188:189], v[188:189], v[202:203]
	v_cvt_pk_bf16_f32 v0, v186, v187
	v_cvt_pk_bf16_f32 v1, v188, v189
	global_store_dwordx2 v253, v[0:1], s[100:101] offset:0
	v_lshlrev_b32_e32 v96, 16, v72
	v_and_b32_e32 v97, 0xffff0000, v72
	v_lshlrev_b32_e32 v98, 16, v73
	v_and_b32_e32 v99, 0xffff0000, v73
	v_pk_add_f32 v[190:191], v[112:113], v[190:191] op_sel_hi:[0,1]
	v_pk_add_f32 v[192:193], v[112:113], v[192:193] op_sel_hi:[0,1]
	v_pk_mul_f32 v[190:191], v[96:97], v[190:191]
	v_pk_mul_f32 v[192:193], v[98:99], v[192:193]
	v_pk_fma_f32 v[202:203], v[190:191], v[190:191], v[202:203]
	v_pk_fma_f32 v[202:203], v[192:193], v[192:193], v[202:203]
	v_cvt_pk_bf16_f32 v46, v190, v191
	v_cvt_pk_bf16_f32 v47, v192, v193
	global_store_dwordx2 v253, v[46:47], s[100:101] offset:32
	s_waitcnt lgkmcnt(0)
	ds_read_b128 v[212:215], v100 offset:43520
	ds_read_b128 v[228:231], v100 offset:47872
	s_cmp_lt_u32 s23, 1
	s_cbranch_scc1 .Lsg2_r_5
	ds_read_b128 v[216:219], v100 offset:43584
	ds_read_b128 v[232:235], v100 offset:47936
	s_cmp_lt_u32 s23, 2
	s_cbranch_scc1 .Lsg2_r_5
	ds_read_b128 v[220:223], v100 offset:43648
	ds_read_b128 v[236:239], v100 offset:48000
	s_cmp_lt_u32 s23, 3
	s_cbranch_scc1 .Lsg2_r_5
	ds_read_b128 v[224:227], v100 offset:43712
	ds_read_b128 v[240:243], v100 offset:48064

; __device__ __forceinline__ void ss_add(ss_t* p, float sq) { const float fl = floorf(sq); const unsigned hi = (unsigned)fl, lo = (unsigned)((sq - fl) * 4294967296.0f); atomicAdd(p, ((ss_t)hi << 32) | (ss_t)lo); }
; __device__ __forceinline__ unsigned pkbf(float lo, float hi) { typedef float f2_t __attribute__((ext_vector_type(2))); typedef __bf16 b2_t __attribute__((ext_vector_type(2))); f2_t v = {lo, hi}; b2_t b = __builtin_convertvector(v, b2_t); return __builtin_bit_cast(unsigned, b); }
; __device__ __forceinline__ float bflo(unsigned w) { return __uint_as_float(w << 16); }
; __device__ __forceinline__ float bfhi(unsigned w) { return __uint_as_float(w & 0xffff0000u); }
; #define MFMA16(a, b, c) __builtin_amdgcn_mfma_f32_16x16x32_bf16((a), (b), (c), 0, 0, 0)
; __device__ __forceinline__ void mixer_phase256(const Args& A, int l, int vc, const bf16* Z, bf16* MIX, ss_t* ssa, ss_t* ssb, unsigned char* lds, int tid, int wid, int lane) {
;     ...
;         for (int j = 0; j < 4; ++j) {
;             const bf16* vn = VN + j * 64 * VN_STRIDE; const size_t tok = (size_t)((cb + j) * 128 + st); float sq = 0.f;
; #pragma unroll
;             for (int dt = 0; dt < 4; ++dt) {
;                 f32x4 acc = (f32x4){0.f, 0.f, 0.f, 0.f};
; #pragma unroll
;                 for (int ks = 0; ks < 4; ++ks) if (ks < nks) { const bf16x8 a = *(const bf16x8*)(vn + (16 * dt + fr) * VN_STRIDE + 32 * ks + 8 * fq); acc = MFMA16(a, bfr[ks], acc); }
;                 const float v0 = bflo(uw[j][dt].x) * (acc[0] + sbias), v1 = bfhi(uw[j][dt].x) * (acc[1] + sbias), v2 = bflo(uw[j][dt].y) * (acc[2] + sbias), v3 = bfhi(uw[j][dt].y) * (acc[3] + sbias);
;                 sq += (v0 * v0 + v1 * v1) + (v2 * v2 + v3 * v3);
;                 u32x2 w; w.x = pkbf(v0, v1); w.y = pkbf(v2, v3);
;                 *(u32x2*)(MIX + tok * DM + h * 64 + 16 * dt + 4 * fq) = w;
;             }
;             sq += __shfl_xor(sq, 16); sq += __shfl_xor(sq, 32); if (fq == 0) ss_add(ssa + tok, sq);
.Lsg2_m_4:
	s_nop 3
	v_lshlrev_b32_e32 v96, 16, v70
	v_and_b32_e32 v97, 0xffff0000, v70
	v_lshlrev_b32_e32 v98, 16, v71
	v_and_b32_e32 v99, 0xffff0000, v71
	v_pk_add_f32 v[194:195], v[112:113], v[194:195] op_sel_hi:[0,1]
	v_pk_add_f32 v[196:197], v[112:113], v[196:197] op_sel_hi:[0,1]
	v_pk_mul_f32 v[194:195], v[96:97], v[194:195]
	v_pk_mul_f32 v[196:197], v[98:99], v[196:197]
	v_pk_fma_f32 v[202:203], v[194:195], v[194:195], v[202:203]
	v_pk_fma_f32 v[202:203], v[196:197], v[196:197], v[202:203]
	v_cvt_pk_bf16_f32 v0, v194, v195
	v_cvt_pk_bf16_f32 v1, v196, v197
	global_store_dwordx2 v253, v[0:1], s[100:101] offset:64
	v_lshlrev_b32_e32 v96, 16, v68
	v_and_b32_e32 v97, 0xffff0000, v68
	v_lshlrev_b32_e32 v98, 16, v69
	v_and_b32_e32 v99, 0xffff0000, v69
	v_pk_add_f32 v[198:199], v[112:113], v[198:199] op_sel_hi:[0,1]
	v_pk_add_f32 v[200:201], v[112:113], v[200:201] op_sel_hi:[0,1]
	v_pk_mul_f32 v[198:199], v[96:97], v[198:199]
	v_pk_mul_f32 v[200:201], v[98:99], v[200:201]
	v_pk_fma_f32 v[202:203], v[198:199], v[198:199], v[202:203]
	v_pk_fma_f32 v[202:203], v[200:201], v[200:201], v[202:203]
	v_cvt_pk_bf16_f32 v46, v198, v199
	v_cvt_pk_bf16_f32 v47, v200, v201
	global_store_dwordx2 v253, v[46:47], s[100:101] offset:96
	v_add_f32_e32 v3, v202, v203
	ds_bpermute_b32 v45, v56, v3
	s_waitcnt lgkmcnt(0)
	v_add_f32_e32 v3, v3, v45
	ds_bpermute_b32 v45, v57, v3
	s_waitcnt lgkmcnt(0)
	v_add_f32_e32 v3, v3, v45
	s_mov_b64 exec, s[24:25]
	v_floor_f32_e32 v45, v3
	v_sub_f32_e32 v3, v3, v45
	v_mul_f32_e32 v3, 0x4f800000, v3
	v_cvt_u32_f32_e32 v79, v45
	v_cvt_u32_f32_e32 v78, v3
	global_atomic_add_x2 v254, v[78:79], s[100:101] offset:1024
	s_mov_b64 exec, -1
	v_add_u32_e32 v253, 0x80000, v253
	s_waitcnt lgkmcnt(0)
	ds_read_b128 v[12:15], v100 offset:52224
	ds_read_b128 v[28:31], v100 offset:56576
	s_cmp_lt_u32 s23, 1
	s_cbranch_scc1 .Lsg2_r_6
	ds_read_b128 v[16:19], v100 offset:52288
	ds_read_b128 v[32:35], v100 offset:56640
	s_cmp_lt_u32 s23, 2
	s_cbranch_scc1 .Lsg2_r_6
	ds_read_b128 v[20:23], v100 offset:52352
	ds_read_b128 v[36:39], v100 offset:56704
	s_cmp_lt_u32 s23, 3
	s_cbranch_scc1 .Lsg2_r_6
	ds_read_b128 v[24:27], v100 offset:52416
	ds_read_b128 v[40:43], v100 offset:56768

; __device__ __forceinline__ unsigned pkbf(float lo, float hi) { typedef float f2_t __attribute__((ext_vector_type(2))); typedef __bf16 b2_t __attribute__((ext_vector_type(2))); f2_t v = {lo, hi}; b2_t b = __builtin_convertvector(v, b2_t); return __builtin_bit_cast(unsigned, b); }
; __device__ __forceinline__ float bflo(unsigned w) { return __uint_as_float(w << 16); }
; __device__ __forceinline__ float bfhi(unsigned w) { return __uint_as_float(w & 0xffff0000u); }
; #define MFMA16(a, b, c) __builtin_amdgcn_mfma_f32_16x16x32_bf16((a), (b), (c), 0, 0, 0)
; __device__ __forceinline__ void mixer_phase256(const Args& A, int l, int vc, const bf16* Z, bf16* MIX, ss_t* ssa, ss_t* ssb, unsigned char* lds, int tid, int wid, int lane) {
;     ...
;         for (int j = 0; j < 4; ++j) {
;             const bf16* vn = VN + j * 64 * VN_STRIDE; const size_t tok = (size_t)((cb + j) * 128 + st); float sq = 0.f;
; #pragma unroll
;             for (int dt = 0; dt < 4; ++dt) {
;                 f32x4 acc = (f32x4){0.f, 0.f, 0.f, 0.f};
; #pragma unroll
;                 for (int ks = 0; ks < 4; ++ks) if (ks < nks) { const bf16x8 a = *(const bf16x8*)(vn + (16 * dt + fr) * VN_STRIDE + 32 * ks + 8 * fq); acc = MFMA16(a, bfr[ks], acc); }
;                 const float v0 = bflo(uw[j][dt].x) * (acc[0] + sbias), v1 = bfhi(uw[j][dt].x) * (acc[1] + sbias), v2 = bflo(uw[j][dt].y) * (acc[2] + sbias), v3 = bfhi(uw[j][dt].y) * (acc[3] + sbias);
;                 sq += (v0 * v0 + v1 * v1) + (v2 * v2 + v3 * v3);
;                 u32x2 w; w.x = pkbf(v0, v1); w.y = pkbf(v2, v3);
;                 *(u32x2*)(MIX + tok * DM + h * 64 + 16 * dt + 4 * fq) = w;
.Lsg2_m_5:
	s_nop 3
	v_lshlrev_b32_e32 v96, 16, v64
	v_and_b32_e32 v97, 0xffff0000, v64
	v_lshlrev_b32_e32 v98, 16, v65
	v_and_b32_e32 v99, 0xffff0000, v65
	v_pk_add_f32 v[186:187], v[112:113], v[186:187] op_sel_hi:[0,1]
	v_pk_add_f32 v[188:189], v[112:113], v[188:189] op_sel_hi:[0,1]
	v_pk_mul_f32 v[186:187], v[96:97], v[186:187]
	v_pk_mul_f32 v[188:189], v[98:99], v[188:189]
	v_pk_mul_f32 v[202:203], v[186:187], v[186:187]
	v_pk_fma_f32 v[202:203], v[188:189], v[188:189], v[202:203]
	v_cvt_pk_bf16_f32 v0, v186, v187
	v_cvt_pk_bf16_f32 v1, v188, v189
	global_store_dwordx2 v253, v[0:1], s[100:101] offset:0
	v_lshlrev_b32_e32 v96, 16, v62
	v_and_b32_e32 v97, 0xffff0000, v62
	v_lshlrev_b32_e32 v98, 16, v63
	v_and_b32_e32 v99, 0xffff0000, v63
	v_pk_add_f32 v[190:191], v[112:113], v[190:191] op_sel_hi:[0,1]
	v_pk_add_f32 v[192:193], v[112:113], v[192:193] op_sel_hi:[0,1]
	v_pk_mul_f32 v[190:191], v[96:97], v[190:191]
	v_pk_mul_f32 v[192:193], v[98:99], v[192:193]
	v_pk_fma_f32 v[202:203], v[190:191], v[190:191], v[202:203]
	v_pk_fma_f32 v[202:203], v[192:193], v[192:193], v[202:203]
	v_cvt_pk_bf16_f32 v46, v190, v191
	v_cvt_pk_bf16_f32 v47, v192, v193
	global_store_dwordx2 v253, v[46:47], s[100:101] offset:32
	s_waitcnt lgkmcnt(0)
	ds_read_b128 v[212:215], v100 offset:60928
	ds_read_b128 v[228:231], v100 offset:65280
	s_cmp_lt_u32 s23, 1
	s_cbranch_scc1 .Lsg2_r_7
	ds_read_b128 v[216:219], v100 offset:60992
	ds_read_b128 v[232:235], v100 offset:65344
	s_cmp_lt_u32 s23, 2
	s_cbranch_scc1 .Lsg2_r_7
	ds_read_b128 v[220:223], v100 offset:61056
	ds_read_b128 v[236:239], v100 offset:65408
	s_cmp_lt_u32 s23, 3
	s_cbranch_scc1 .Lsg2_r_7
	ds_read_b128 v[224:227], v100 offset:61120
	ds_read_b128 v[240:243], v100 offset:65472

; __device__ __forceinline__ void ss_add(ss_t* p, float sq) { const float fl = floorf(sq); const unsigned hi = (unsigned)fl, lo = (unsigned)((sq - fl) * 4294967296.0f); atomicAdd(p, ((ss_t)hi << 32) | (ss_t)lo); }
; __device__ __forceinline__ unsigned pkbf(float lo, float hi) { typedef float f2_t __attribute__((ext_vector_type(2))); typedef __bf16 b2_t __attribute__((ext_vector_type(2))); f2_t v = {lo, hi}; b2_t b = __builtin_convertvector(v, b2_t); return __builtin_bit_cast(unsigned, b); }
; __device__ __forceinline__ float bflo(unsigned w) { return __uint_as_float(w << 16); }
; __device__ __forceinline__ float bfhi(unsigned w) { return __uint_as_float(w & 0xffff0000u); }
; #define MFMA16(a, b, c) __builtin_amdgcn_mfma_f32_16x16x32_bf16((a), (b), (c), 0, 0, 0)
; __device__ __forceinline__ void mixer_phase256(const Args& A, int l, int vc, const bf16* Z, bf16* MIX, ss_t* ssa, ss_t* ssb, unsigned char* lds, int tid, int wid, int lane) {
;     ...
;         for (int j = 0; j < 4; ++j) {
;             const bf16* vn = VN + j * 64 * VN_STRIDE; const size_t tok = (size_t)((cb + j) * 128 + st); float sq = 0.f;
; #pragma unroll
;             for (int dt = 0; dt < 4; ++dt) {
;                 f32x4 acc = (f32x4){0.f, 0.f, 0.f, 0.f};
; #pragma unroll
;                 for (int ks = 0; ks < 4; ++ks) if (ks < nks) { const bf16x8 a = *(const bf16x8*)(vn + (16 * dt + fr) * VN_STRIDE + 32 * ks + 8 * fq); acc = MFMA16(a, bfr[ks], acc); }
;                 const float v0 = bflo(uw[j][dt].x) * (acc[0] + sbias), v1 = bfhi(uw[j][dt].x) * (acc[1] + sbias), v2 = bflo(uw[j][dt].y) * (acc[2] + sbias), v3 = bfhi(uw[j][dt].y) * (acc[3] + sbias);
;                 sq += (v0 * v0 + v1 * v1) + (v2 * v2 + v3 * v3);
;                 u32x2 w; w.x = pkbf(v0, v1); w.y = pkbf(v2, v3);
;                 *(u32x2*)(MIX + tok * DM + h * 64 + 16 * dt + 4 * fq) = w;
;             }
;             sq += __shfl_xor(sq, 16); sq += __shfl_xor(sq, 32); if (fq == 0) ss_add(ssa + tok, sq);
.Lsg2_m_6:
	s_nop 3
	v_lshlrev_b32_e32 v96, 16, v60
	v_and_b32_e32 v97, 0xffff0000, v60
	v_lshlrev_b32_e32 v98, 16, v61
	v_and_b32_e32 v99, 0xffff0000, v61
	v_pk_add_f32 v[194:195], v[112:113], v[194:195] op_sel_hi:[0,1]
	v_pk_add_f32 v[196:197], v[112:113], v[196:197] op_sel_hi:[0,1]
	v_pk_mul_f32 v[194:195], v[96:97], v[194:195]
	v_pk_mul_f32 v[196:197], v[98:99], v[196:197]
	v_pk_fma_f32 v[202:203], v[194:195], v[194:195], v[202:203]
	v_pk_fma_f32 v[202:203], v[196:197], v[196:197], v[202:203]
	v_cvt_pk_bf16_f32 v0, v194, v195
	v_cvt_pk_bf16_f32 v1, v196, v197
	global_store_dwordx2 v253, v[0:1], s[100:101] offset:64
	v_lshlrev_b32_e32 v96, 16, v58
	v_and_b32_e32 v97, 0xffff0000, v58
	v_lshlrev_b32_e32 v98, 16, v59
	v_and_b32_e32 v99, 0xffff0000, v59
	v_pk_add_f32 v[198:199], v[112:113], v[198:199] op_sel_hi:[0,1]
	v_pk_add_f32 v[200:201], v[112:113], v[200:201] op_sel_hi:[0,1]
	v_pk_mul_f32 v[198:199], v[96:97], v[198:199]
	v_pk_mul_f32 v[200:201], v[98:99], v[200:201]
	v_pk_fma_f32 v[202:203], v[198:199], v[198:199], v[202:203]
	v_pk_fma_f32 v[202:203], v[200:201], v[200:201], v[202:203]
	v_cvt_pk_bf16_f32 v46, v198, v199
	v_cvt_pk_bf16_f32 v47, v200, v201
	global_store_dwordx2 v253, v[46:47], s[100:101] offset:96
	v_add_f32_e32 v3, v202, v203
	ds_bpermute_b32 v45, v56, v3
	s_waitcnt lgkmcnt(0)
	v_add_f32_e32 v3, v3, v45
	ds_bpermute_b32 v45, v57, v3
	s_waitcnt lgkmcnt(0)
	v_add_f32_e32 v3, v3, v45
	s_mov_b64 exec, s[24:25]
	v_floor_f32_e32 v45, v3
	v_sub_f32_e32 v3, v3, v45
	v_mul_f32_e32 v3, 0x4f800000, v3
	v_cvt_u32_f32_e32 v79, v45
	v_cvt_u32_f32_e32 v78, v3
	global_atomic_add_x2 v254, v[78:79], s[100:101] offset:2048
	s_mov_b64 exec, -1
	v_add_u32_e32 v253, 0x80000, v253
	s_waitcnt lgkmcnt(0)
	v_mfma_f32_16x16x32_bf16 v[194:197], v[212:215], v[4:7], 0
	v_mfma_f32_16x16x32_bf16 v[198:201], v[228:231], v[4:7], 0
	s_cmp_lt_u32 s23, 1
	s_cbranch_scc1 .Lsg2_m_7
	v_mfma_f32_16x16x32_bf16 v[194:197], v[216:219], v[8:11], v[194:197]
	v_mfma_f32_16x16x32_bf16 v[198:201], v[232:235], v[8:11], v[198:201]
	s_cmp_lt_u32 s23, 2
	s_cbranch_scc1 .Lsg2_m_7
	v_mfma_f32_16x16x32_bf16 v[194:197], v[220:223], v[88:91], v[194:197]
	v_mfma_f32_16x16x32_bf16 v[198:201], v[236:239], v[88:91], v[198:201]
	s_cmp_lt_u32 s23, 3
	s_cbranch_scc1 .Lsg2_m_7
	v_mfma_f32_16x16x32_bf16 v[194:197], v[224:227], v[92:95], v[194:197]
	v_mfma_f32_16x16x32_bf16 v[198:201], v[240:243], v[92:95], v[198:201]
.Lsg2_m_7:
	s_nop 3
	v_lshlrev_b32_e32 v96, 16, v54
	v_and_b32_e32 v97, 0xffff0000, v54
	v_lshlrev_b32_e32 v98, 16, v55
	v_and_b32_e32 v99, 0xffff0000, v55
	v_pk_add_f32 v[186:187], v[112:113], v[186:187] op_sel_hi:[0,1]
	v_pk_add_f32 v[188:189], v[112:113], v[188:189] op_sel_hi:[0,1]
	v_pk_mul_f32 v[186:187], v[96:97], v[186:187]
	v_pk_mul_f32 v[188:189], v[98:99], v[188:189]
	v_pk_mul_f32 v[202:203], v[186:187], v[186:187]
	v_pk_fma_f32 v[202:203], v[188:189], v[188:189], v[202:203]
	v_cvt_pk_bf16_f32 v0, v186, v187
	v_cvt_pk_bf16_f32 v1, v188, v189
	global_store_dwordx2 v253, v[0:1], s[100:101] offset:0
	v_lshlrev_b32_e32 v96, 16, v52
	v_and_b32_e32 v97, 0xffff0000, v52
	v_lshlrev_b32_e32 v98, 16, v53
	v_and_b32_e32 v99, 0xffff0000, v53
	v_pk_add_f32 v[190:191], v[112:113], v[190:191] op_sel_hi:[0,1]
	v_pk_add_f32 v[192:193], v[112:113], v[192:193] op_sel_hi:[0,1]
	v_pk_mul_f32 v[190:191], v[96:97], v[190:191]
	v_pk_mul_f32 v[192:193], v[98:99], v[192:193]
	v_pk_fma_f32 v[202:203], v[190:191], v[190:191], v[202:203]
	v_pk_fma_f32 v[202:203], v[192:193], v[192:193], v[202:203]
	v_cvt_pk_bf16_f32 v46, v190, v191
	v_cvt_pk_bf16_f32 v47, v192, v193
	global_store_dwordx2 v253, v[46:47], s[100:101] offset:32
	s_nop 7
	s_nop 0
	v_lshlrev_b32_e32 v96, 16, v50
	v_and_b32_e32 v97, 0xffff0000, v50
	v_lshlrev_b32_e32 v98, 16, v51
	v_and_b32_e32 v99, 0xffff0000, v51
	v_pk_add_f32 v[194:195], v[112:113], v[194:195] op_sel_hi:[0,1]
	v_pk_add_f32 v[196:197], v[112:113], v[196:197] op_sel_hi:[0,1]
	v_pk_mul_f32 v[194:195], v[96:97], v[194:195]
	v_pk_mul_f32 v[196:197], v[98:99], v[196:197]
	v_pk_fma_f32 v[202:203], v[194:195], v[194:195], v[202:203]
	v_pk_fma_f32 v[202:203], v[196:197], v[196:197], v[202:203]
	v_cvt_pk_bf16_f32 v0, v194, v195
	v_cvt_pk_bf16_f32 v1, v196, v197
	global_store_dwordx2 v253, v[0:1], s[100:101] offset:64
	v_lshlrev_b32_e32 v96, 16, v48
	v_and_b32_e32 v97, 0xffff0000, v48
	v_lshlrev_b32_e32 v98, 16, v49
	v_and_b32_e32 v99, 0xffff0000, v49
	v_pk_add_f32 v[198:199], v[112:113], v[198:199] op_sel_hi:[0,1]
	v_pk_add_f32 v[200:201], v[112:113], v[200:201] op_sel_hi:[0,1]
	v_pk_mul_f32 v[198:199], v[96:97], v[198:199]
	v_pk_mul_f32 v[200:201], v[98:99], v[200:201]
	v_pk_fma_f32 v[202:203], v[198:199], v[198:199], v[202:203]
	v_pk_fma_f32 v[202:203], v[200:201], v[200:201], v[202:203]
	v_cvt_pk_bf16_f32 v46, v198, v199
	v_cvt_pk_bf16_f32 v47, v200, v201
	global_store_dwordx2 v253, v[46:47], s[100:101] offset:96
	v_add_f32_e32 v3, v202, v203
	ds_bpermute_b32 v45, v56, v3
	s_waitcnt lgkmcnt(0)
	v_add_f32_e32 v3, v3, v45
	ds_bpermute_b32 v45, v57, v3
	s_waitcnt lgkmcnt(0)
	v_add_f32_e32 v3, v3, v45
	s_mov_b64 exec, s[24:25]
	v_floor_f32_e32 v45, v3
	v_sub_f32_e32 v3, v3, v45
	v_mul_f32_e32 v3, 0x4f800000, v3
	v_cvt_u32_f32_e32 v79, v45
	v_cvt_u32_f32_e32 v78, v3
	global_atomic_add_x2 v254, v[78:79], s[100:101] offset:3072
	s_mov_b64 exec, -1
	s_branch .Lsg2_done

; __device__ __forceinline__ unsigned pkbf(float lo, float hi) { typedef float f2_t __attribute__((ext_vector_type(2))); typedef __bf16 b2_t __attribute__((ext_vector_type(2))); f2_t v = {lo, hi}; b2_t b = __builtin_convertvector(v, b2_t); return __builtin_bit_cast(unsigned, b); }
; __device__ __forceinline__ float bflo(unsigned w) { return __uint_as_float(w << 16); }
; __device__ __forceinline__ float bfhi(unsigned w) { return __uint_as_float(w & 0xffff0000u); }
; template <int PAR> __device__ __forceinline__ void attn_sub(const bf16* KS, const bf16* VT, const float* BTg, const float* gq, float sink2, int n, int ti, int hq, const u32x4 w0, const u32x4 w1, bf16* MIX, ss_t* ssb, int lane) {
;     const int fr = lane & 15, fq = lane >> 4; const int qi = 16 * ti + fr, tb = ti - PAR; const int tok = n * 128 + qi;
;     bf16x8 qf[2];
;     { float f0[8], f1[8]; float ss = 0.f;
; #pragma unroll
;       for (int e = 0; e < 4; ++e) { f0[2 * e] = bflo(w0[e]); f0[2 * e + 1] = bfhi(w0[e]); f1[2 * e] = bflo(w1[e]); f1[2 * e + 1] = bfhi(w1[e]);
;           ss += (f0[2 * e] * f0[2 * e] + f0[2 * e + 1] * f0[2 * e + 1]) + (f1[2 * e] * f1[2 * e] + f1[2 * e + 1] * f1[2 * e + 1]); }
;       ss += __shfl_xor(ss, 16); ss += __shfl_xor(ss, 32);
;       const float rs = (0.125f * 1.4426950408889634f) / sqrtf(ss * (1.0f / 64.f) + EPS);
;       const f32x4 a0 = *(const f32x4*)(gq + 8 * fq), a1 = *(const f32x4*)(gq + 8 * fq + 4), b0 = *(const f32x4*)(gq + 32 + 8 * fq), b1 = *(const f32x4*)(gq + 32 + 8 * fq + 4);
;       u32x4 p0, p1;
;       p0.x = pkbf(f0[0] * rs * a0.x, f0[1] * rs * a0.y); p0.y = pkbf(f0[2] * rs * a0.z, f0[3] * rs * a0.w); p0.z = pkbf(f0[4] * rs * a1.x, f0[5] * rs * a1.y); p0.w = pkbf(f0[6] * rs * a1.z, f0[7] * rs * a1.w);
;       p1.x = pkbf(f1[0] * rs * b0.x, f1[1] * rs * b0.y); p1.y = pkbf(f1[2] * rs * b0.z, f1[3] * rs * b0.w); p1.z = pkbf(f1[4] * rs * b1.x, f1[5] * rs * b1.y); p1.w = pkbf(f1[6] * rs * b1.z, f1[7] * rs * b1.w);
;       qf[0] = __builtin_bit_cast(bf16x8, p0); qf[1] = __builtin_bit_cast(bf16x8, p1); }
;     const int e0 = 4 * fq - fr;
;     const float* bp = BTg + (128 - 16 * 8 - 3 - e0);
.Lsg2_done:
	v_readlane_b32 s100, v250, 28
	v_readlane_b32 s101, v250, 29
	v_readlane_b32 s24, v249, 63
	v_readlane_b32 s23, v248, 1
	s_lshr_b32 s20, s73, 1
	s_and_b32 s21, s73, 1
	s_lshl_b32 s26, s21, 2
	v_and_b32_e32 v200, 15, v174
	v_lshrrev_b32_e32 v201, 4, v174
	s_add_i32 s22, s24, s20
	s_cmp_gt_i32 s23, 0
	s_cselect_b64 s[36:37], -1, 0
	v_lshlrev_b32_e32 v202, 2, v201
	v_add_u32_e32 v203, 0, v202
	v_cmp_gt_i32_e64 s[40:41], v203, v200
	v_add_u32_e32 v203, 1, v202
	v_cmp_gt_i32_e64 s[42:43], v203, v200
	v_add_u32_e32 v203, 2, v202
	v_cmp_gt_i32_e64 s[44:45], v203, v200
	v_add_u32_e32 v203, 3, v202
	v_cmp_gt_i32_e64 s[46:47], v203, v200
	v_cmp_eq_u32_e64 s[56:57], 0, v201
	v_mov_b32_e32 v203, s21
	v_lshl_add_u32 v185, v203, 6, v200
	v_mul_u32_u24_e32 v185, 0x90, v185
	v_lshl_add_u32 v185, v201, 4, v185
	v_lshlrev_b32_e32 v186, 2, v200
	v_lshlrev_b32_e32 v0, 4, v201
	v_sub_u32_e32 v186, v186, v0
	s_lshl_b32 s27, s20, 9
	s_add_i32 s27, s27, 0x113f4
	v_add_u32_e32 v186, s27, v186
	v_mul_u32_u24_e32 v187, 0x210, v200
	v_lshl_add_u32 v187, v203, 7, v187
	v_lshl_add_u32 v187, v201, 3, v187
	v_add_u32_e32 v187, 0x9000, v187
	v_add_u32_e32 v188, 0x2100, v187
	v_add_u32_e32 v189, 0x4200, v187
	v_add_u32_e32 v190, 0x6300, v187
	v_lshl_add_u32 v0, v203, 6, v200
	v_add_u32_e32 v0, s23, v0
	v_lshlrev_b32_e32 v191, 12, v0
	s_lshl_b32 s27, s22, 7
	s_add_i32 s27, s27, 0x1ba00800
	v_add_u32_e32 v191, s27, v191
	v_lshl_add_u32 v191, v201, 3, v191
	s_add_i32 s27, s78, 13
	s_lshl_b32 s27, s27, 16
	v_lshl_add_u32 v192, v0, 3, s27
	v_xor_b32_e32 v193, 16, v174
	v_lshlrev_b32_e32 v193, 2, v193
	v_xor_b32_e32 v194, 32, v174
	v_lshlrev_b32_e32 v194, 2, v194
	v_mov_b32_e32 v195, 0xf149f2ca
	v_mul_f32_e32 v184, 0x3fb8aa3b, v184
	v_lshlrev_b32_e32 v4, 16, v116
	v_and_b32_e32 v5, 0xffff0000, v116
	v_lshlrev_b32_e32 v6, 16, v117
	v_and_b32_e32 v7, 0xffff0000, v117
	v_lshlrev_b32_e32 v8, 16, v118
	v_and_b32_e32 v9, 0xffff0000, v118
	v_lshlrev_b32_e32 v10, 16, v119
	v_and_b32_e32 v11, 0xffff0000, v119
	v_lshlrev_b32_e32 v12, 16, v120
	v_and_b32_e32 v13, 0xffff0000, v120
	v_lshlrev_b32_e32 v14, 16, v121
	v_and_b32_e32 v15, 0xffff0000, v121
	v_lshlrev_b32_e32 v16, 16, v122
	v_and_b32_e32 v17, 0xffff0000, v122
	v_lshlrev_b32_e32 v18, 16, v123
	v_and_b32_e32 v19, 0xffff0000, v123
	v_pk_mul_f32 v[78:79], v[4:5], v[4:5]
	v_pk_fma_f32 v[78:79], v[6:7], v[6:7], v[78:79]
	v_pk_fma_f32 v[78:79], v[8:9], v[8:9], v[78:79]
	v_pk_fma_f32 v[78:79], v[10:11], v[10:11], v[78:79]
	v_pk_fma_f32 v[78:79], v[12:13], v[12:13], v[78:79]
	v_pk_fma_f32 v[78:79], v[14:15], v[14:15], v[78:79]
	v_pk_fma_f32 v[78:79], v[16:17], v[16:17], v[78:79]
	v_pk_fma_f32 v[78:79], v[18:19], v[18:19], v[78:79]
	v_add_f32_e32 v45, v78, v79
	v_lshlrev_b32_e32 v20, 16, v124
	v_and_b32_e32 v21, 0xffff0000, v124
	v_lshlrev_b32_e32 v22, 16, v125
	v_and_b32_e32 v23, 0xffff0000, v125
	v_lshlrev_b32_e32 v24, 16, v126
	v_and_b32_e32 v25, 0xffff0000, v126
	v_lshlrev_b32_e32 v26, 16, v127
	v_and_b32_e32 v27, 0xffff0000, v127
	v_lshlrev_b32_e32 v28, 16, v128
	v_and_b32_e32 v29, 0xffff0000, v128
	v_lshlrev_b32_e32 v30, 16, v129
	v_and_b32_e32 v31, 0xffff0000, v129
	v_lshlrev_b32_e32 v32, 16, v130
	v_and_b32_e32 v33, 0xffff0000, v130
	v_lshlrev_b32_e32 v34, 16, v131
	v_and_b32_e32 v35, 0xffff0000, v131
	v_pk_mul_f32 v[80:81], v[20:21], v[20:21]
	v_pk_fma_f32 v[80:81], v[22:23], v[22:23], v[80:81]
	v_pk_fma_f32 v[80:81], v[24:25], v[24:25], v[80:81]
	v_pk_fma_f32 v[80:81], v[26:27], v[26:27], v[80:81]
	v_pk_fma_f32 v[80:81], v[28:29], v[28:29], v[80:81]
	v_pk_fma_f32 v[80:81], v[30:31], v[30:31], v[80:81]
	v_pk_fma_f32 v[80:81], v[32:33], v[32:33], v[80:81]
	v_pk_fma_f32 v[80:81], v[34:35], v[34:35], v[80:81]
	v_add_f32_e32 v46, v80, v81
	v_lshlrev_b32_e32 v212, 16, v132
	v_and_b32_e32 v213, 0xffff0000, v132
	v_lshlrev_b32_e32 v214, 16, v133
	v_and_b32_e32 v215, 0xffff0000, v133
	v_lshlrev_b32_e32 v216, 16, v134
	v_and_b32_e32 v217, 0xffff0000, v134
	v_lshlrev_b32_e32 v218, 16, v135
	v_and_b32_e32 v219, 0xffff0000, v135
	v_lshlrev_b32_e32 v220, 16, v136
	v_and_b32_e32 v221, 0xffff0000, v136
	v_lshlrev_b32_e32 v222, 16, v137
	v_and_b32_e32 v223, 0xffff0000, v137
	v_lshlrev_b32_e32 v224, 16, v138
	v_and_b32_e32 v225, 0xffff0000, v138
	v_lshlrev_b32_e32 v226, 16, v139
	v_and_b32_e32 v227, 0xffff0000, v139
	v_pk_mul_f32 v[96:97], v[212:213], v[212:213]
	v_pk_fma_f32 v[96:97], v[214:215], v[214:215], v[96:97]
	v_pk_fma_f32 v[96:97], v[216:217], v[216:217], v[96:97]
	v_pk_fma_f32 v[96:97], v[218:219], v[218:219], v[96:97]
	v_pk_fma_f32 v[96:97], v[220:221], v[220:221], v[96:97]
	v_pk_fma_f32 v[96:97], v[222:223], v[222:223], v[96:97]
	v_pk_fma_f32 v[96:97], v[224:225], v[224:225], v[96:97]
	v_pk_fma_f32 v[96:97], v[226:227], v[226:227], v[96:97]
	v_add_f32_e32 v47, v96, v97
	v_lshlrev_b32_e32 v228, 16, v140
	v_and_b32_e32 v229, 0xffff0000, v140
	v_lshlrev_b32_e32 v230, 16, v141
	v_and_b32_e32 v231, 0xffff0000, v141
	v_lshlrev_b32_e32 v232, 16, v142
	v_and_b32_e32 v233, 0xffff0000, v142
	v_lshlrev_b32_e32 v234, 16, v143
	v_and_b32_e32 v235, 0xffff0000, v143
	v_lshlrev_b32_e32 v236, 16, v144
	v_and_b32_e32 v237, 0xffff0000, v144
	v_lshlrev_b32_e32 v238, 16, v145
	v_and_b32_e32 v239, 0xffff0000, v145
	v_lshlrev_b32_e32 v240, 16, v146
	v_and_b32_e32 v241, 0xffff0000, v146
	v_lshlrev_b32_e32 v242, 16, v147
	v_and_b32_e32 v243, 0xffff0000, v147
	v_pk_mul_f32 v[98:99], v[228:229], v[228:229]
	v_pk_fma_f32 v[98:99], v[230:231], v[230:231], v[98:99]
	v_pk_fma_f32 v[98:99], v[232:233], v[232:233], v[98:99]
	v_pk_fma_f32 v[98:99], v[234:235], v[234:235], v[98:99]
	v_pk_fma_f32 v[98:99], v[236:237], v[236:237], v[98:99]
	v_pk_fma_f32 v[98:99], v[238:239], v[238:239], v[98:99]
	v_pk_fma_f32 v[98:99], v[240:241], v[240:241], v[98:99]
	v_pk_fma_f32 v[98:99], v[242:243], v[242:243], v[98:99]
	v_add_f32_e32 v76, v98, v99
	ds_bpermute_b32 v0, v193, v45
	ds_bpermute_b32 v1, v193, v46
	ds_bpermute_b32 v3, v193, v47
	ds_bpermute_b32 v100, v193, v76
	s_waitcnt lgkmcnt(0)
; __device__ __forceinline__ unsigned pkbf(float lo, float hi) { typedef float f2_t __attribute__((ext_vector_type(2))); typedef __bf16 b2_t __attribute__((ext_vector_type(2))); f2_t v = {lo, hi}; b2_t b = __builtin_convertvector(v, b2_t); return __builtin_bit_cast(unsigned, b); }
; template <int PAR> __device__ __forceinline__ void attn_sub(const bf16* KS, const bf16* VT, const float* BTg, const float* gq, float sink2, int n, int ti, int hq, const u32x4 w0, const u32x4 w1, bf16* MIX, ss_t* ssb, int lane) {
;     ...
;       ss += __shfl_xor(ss, 16); ss += __shfl_xor(ss, 32);
;       const float rs = (0.125f * 1.4426950408889634f) / sqrtf(ss * (1.0f / 64.f) + EPS);
;       const f32x4 a0 = *(const f32x4*)(gq + 8 * fq), a1 = *(const f32x4*)(gq + 8 * fq + 4), b0 = *(const f32x4*)(gq + 32 + 8 * fq), b1 = *(const f32x4*)(gq + 32 + 8 * fq + 4);
;       u32x4 p0, p1;
;       p0.x = pkbf(f0[0] * rs * a0.x, f0[1] * rs * a0.y); p0.y = pkbf(f0[2] * rs * a0.z, f0[3] * rs * a0.w); p0.z = pkbf(f0[4] * rs * a1.x, f0[5] * rs * a1.y); p0.w = pkbf(f0[6] * rs * a1.z, f0[7] * rs * a1.w);
;       p1.x = pkbf(f1[0] * rs * b0.x, f1[1] * rs * b0.y); p1.y = pkbf(f1[2] * rs * b0.z, f1[3] * rs * b0.w); p1.z = pkbf(f1[4] * rs * b1.x, f1[5] * rs * b1.y); p1.w = pkbf(f1[6] * rs * b1.z, f1[7] * rs * b1.w);
;       qf[0] = __builtin_bit_cast(bf16x8, p0); qf[1] = __builtin_bit_cast(bf16x8, p1); }
;     const int e0 = 4 * fq - fr;
;     const float* bp = BTg + (128 - 16 * 8 - 3 - e0);
;     ...
;             const float v = valid ? acc[r] + bp[16 * (8 - rel) + (3 - r)] : -1e30f; acc[r] = v; mx = fmaxf(mx, v); }
	v_add_f32_e32 v45, v45, v0
	v_add_f32_e32 v46, v46, v1
	v_add_f32_e32 v47, v47, v3
	v_add_f32_e32 v76, v76, v100
	ds_bpermute_b32 v0, v194, v45
	ds_bpermute_b32 v1, v194, v46
	ds_bpermute_b32 v3, v194, v47
	ds_bpermute_b32 v100, v194, v76
	s_waitcnt lgkmcnt(0)
	v_add_f32_e32 v45, v45, v0
	v_add_f32_e32 v46, v46, v1
	v_add_f32_e32 v47, v47, v3
	v_add_f32_e32 v76, v76, v100
	v_fmamk_f32 v45, v45, 0x3c800000, v205
	v_fmamk_f32 v46, v46, 0x3c800000, v205
	v_fmamk_f32 v47, v47, 0x3c800000, v205
	v_fmamk_f32 v76, v76, 0x3c800000, v205
	v_rsq_f32_e32 v45, v45
	v_rsq_f32_e32 v46, v46
	v_rsq_f32_e32 v47, v47
	v_rsq_f32_e32 v76, v76
	s_nop 0
	v_mul_f32_e32 v78, 0x3e38aa3b, v45
	v_mul_f32_e32 v80, 0x3e38aa3b, v46
	v_mul_f32_e32 v96, 0x3e38aa3b, v47
	v_mul_f32_e32 v98, 0x3e38aa3b, v76
	v_pk_mul_f32 v[4:5], v[78:79], v[4:5] op_sel_hi:[0,1]
	v_pk_mul_f32 v[4:5], v[4:5], v[148:149]
	v_cvt_pk_bf16_f32 v116, v4, v5
	v_pk_mul_f32 v[6:7], v[78:79], v[6:7] op_sel_hi:[0,1]
	v_pk_mul_f32 v[6:7], v[6:7], v[150:151]
	v_cvt_pk_bf16_f32 v117, v6, v7
	v_pk_mul_f32 v[8:9], v[78:79], v[8:9] op_sel_hi:[0,1]
	v_pk_mul_f32 v[8:9], v[8:9], v[152:153]
	v_cvt_pk_bf16_f32 v118, v8, v9
	v_pk_mul_f32 v[10:11], v[78:79], v[10:11] op_sel_hi:[0,1]
	v_pk_mul_f32 v[10:11], v[10:11], v[154:155]
	v_cvt_pk_bf16_f32 v119, v10, v11
	v_pk_mul_f32 v[12:13], v[78:79], v[12:13] op_sel_hi:[0,1]
	v_pk_mul_f32 v[12:13], v[12:13], v[156:157]
	v_cvt_pk_bf16_f32 v120, v12, v13
	v_pk_mul_f32 v[14:15], v[78:79], v[14:15] op_sel_hi:[0,1]
	v_pk_mul_f32 v[14:15], v[14:15], v[158:159]
	v_cvt_pk_bf16_f32 v121, v14, v15
	v_pk_mul_f32 v[16:17], v[78:79], v[16:17] op_sel_hi:[0,1]
	v_pk_mul_f32 v[16:17], v[16:17], v[180:181]
	v_cvt_pk_bf16_f32 v122, v16, v17
	v_pk_mul_f32 v[18:19], v[78:79], v[18:19] op_sel_hi:[0,1]
	v_pk_mul_f32 v[18:19], v[18:19], v[182:183]
	v_cvt_pk_bf16_f32 v123, v18, v19
	v_pk_mul_f32 v[20:21], v[80:81], v[20:21] op_sel_hi:[0,1]
	v_pk_mul_f32 v[20:21], v[20:21], v[148:149]
	v_cvt_pk_bf16_f32 v124, v20, v21
	v_pk_mul_f32 v[22:23], v[80:81], v[22:23] op_sel_hi:[0,1]
	v_pk_mul_f32 v[22:23], v[22:23], v[150:151]
	v_cvt_pk_bf16_f32 v125, v22, v23
	v_pk_mul_f32 v[24:25], v[80:81], v[24:25] op_sel_hi:[0,1]
	v_pk_mul_f32 v[24:25], v[24:25], v[152:153]
	v_cvt_pk_bf16_f32 v126, v24, v25
	v_pk_mul_f32 v[26:27], v[80:81], v[26:27] op_sel_hi:[0,1]
	v_pk_mul_f32 v[26:27], v[26:27], v[154:155]
	v_cvt_pk_bf16_f32 v127, v26, v27
	v_pk_mul_f32 v[28:29], v[80:81], v[28:29] op_sel_hi:[0,1]
	v_pk_mul_f32 v[28:29], v[28:29], v[156:157]
	v_cvt_pk_bf16_f32 v128, v28, v29
	v_pk_mul_f32 v[30:31], v[80:81], v[30:31] op_sel_hi:[0,1]
	v_pk_mul_f32 v[30:31], v[30:31], v[158:159]
	v_cvt_pk_bf16_f32 v129, v30, v31
	v_pk_mul_f32 v[32:33], v[80:81], v[32:33] op_sel_hi:[0,1]
	v_pk_mul_f32 v[32:33], v[32:33], v[180:181]
	v_cvt_pk_bf16_f32 v130, v32, v33
	v_pk_mul_f32 v[34:35], v[80:81], v[34:35] op_sel_hi:[0,1]
	v_pk_mul_f32 v[34:35], v[34:35], v[182:183]
	v_cvt_pk_bf16_f32 v131, v34, v35
	v_pk_mul_f32 v[212:213], v[96:97], v[212:213] op_sel_hi:[0,1]
	v_pk_mul_f32 v[212:213], v[212:213], v[148:149]
	v_cvt_pk_bf16_f32 v132, v212, v213
	v_pk_mul_f32 v[214:215], v[96:97], v[214:215] op_sel_hi:[0,1]
	v_pk_mul_f32 v[214:215], v[214:215], v[150:151]
	v_cvt_pk_bf16_f32 v133, v214, v215
	v_pk_mul_f32 v[216:217], v[96:97], v[216:217] op_sel_hi:[0,1]
	v_pk_mul_f32 v[216:217], v[216:217], v[152:153]
	v_cvt_pk_bf16_f32 v134, v216, v217
	v_pk_mul_f32 v[218:219], v[96:97], v[218:219] op_sel_hi:[0,1]
	v_pk_mul_f32 v[218:219], v[218:219], v[154:155]
	v_cvt_pk_bf16_f32 v135, v218, v219
	v_pk_mul_f32 v[220:221], v[96:97], v[220:221] op_sel_hi:[0,1]
	v_pk_mul_f32 v[220:221], v[220:221], v[156:157]
	v_cvt_pk_bf16_f32 v136, v220, v221
	v_pk_mul_f32 v[222:223], v[96:97], v[222:223] op_sel_hi:[0,1]
	v_pk_mul_f32 v[222:223], v[222:223], v[158:159]
	v_cvt_pk_bf16_f32 v137, v222, v223
	v_pk_mul_f32 v[224:225], v[96:97], v[224:225] op_sel_hi:[0,1]
	v_pk_mul_f32 v[224:225], v[224:225], v[180:181]
	v_cvt_pk_bf16_f32 v138, v224, v225
	v_pk_mul_f32 v[226:227], v[96:97], v[226:227] op_sel_hi:[0,1]
	v_pk_mul_f32 v[226:227], v[226:227], v[182:183]
	v_cvt_pk_bf16_f32 v139, v226, v227
	v_pk_mul_f32 v[228:229], v[98:99], v[228:229] op_sel_hi:[0,1]
	v_pk_mul_f32 v[228:229], v[228:229], v[148:149]
	v_cvt_pk_bf16_f32 v140, v228, v229
	v_pk_mul_f32 v[230:231], v[98:99], v[230:231] op_sel_hi:[0,1]
	v_pk_mul_f32 v[230:231], v[230:231], v[150:151]
	v_cvt_pk_bf16_f32 v141, v230, v231
	v_pk_mul_f32 v[232:233], v[98:99], v[232:233] op_sel_hi:[0,1]
	v_pk_mul_f32 v[232:233], v[232:233], v[152:153]
	v_cvt_pk_bf16_f32 v142, v232, v233
	v_pk_mul_f32 v[234:235], v[98:99], v[234:235] op_sel_hi:[0,1]
	v_pk_mul_f32 v[234:235], v[234:235], v[154:155]
	v_cvt_pk_bf16_f32 v143, v234, v235
	v_pk_mul_f32 v[236:237], v[98:99], v[236:237] op_sel_hi:[0,1]
	v_pk_mul_f32 v[236:237], v[236:237], v[156:157]
	v_cvt_pk_bf16_f32 v144, v236, v237
	v_pk_mul_f32 v[238:239], v[98:99], v[238:239] op_sel_hi:[0,1]
	v_pk_mul_f32 v[238:239], v[238:239], v[158:159]
	v_cvt_pk_bf16_f32 v145, v238, v239
	v_pk_mul_f32 v[240:241], v[98:99], v[240:241] op_sel_hi:[0,1]
	v_pk_mul_f32 v[240:241], v[240:241], v[180:181]
	v_cvt_pk_bf16_f32 v146, v240, v241
	v_pk_mul_f32 v[242:243], v[98:99], v[242:243] op_sel_hi:[0,1]
	v_pk_mul_f32 v[242:243], v[242:243], v[182:183]
	v_cvt_pk_bf16_f32 v147, v242, v243
	ds_read2_b32 v[84:85], v186 offset0:131 offset1:130
	ds_read2_b32 v[86:87], v186 offset0:129 offset1:128
	ds_read2_b32 v[88:89], v186 offset0:115 offset1:114
	ds_read2_b32 v[90:91], v186 offset0:113 offset1:112
	ds_read2_b32 v[92:93], v186 offset0:99 offset1:98
	ds_read2_b32 v[94:95], v186 offset0:97 offset1:96
	ds_read2_b32 v[96:97], v186 offset0:83 offset1:82
	ds_read2_b32 v[98:99], v186 offset0:81 offset1:80
	ds_read2_b32 v[40:41], v186 offset0:67 offset1:66
	ds_read2_b32 v[42:43], v186 offset0:65 offset1:64
	s_waitcnt lgkmcnt(0)
; #define MFMA16(a, b, c) __builtin_amdgcn_mfma_f32_16x16x32_bf16((a), (b), (c), 0, 0, 0)
; template <int PAR> __device__ __forceinline__ void attn_sub(const bf16* KS, const bf16* VT, const float* BTg, const float* gq, float sink2, int n, int ti, int hq, const u32x4 w0, const u32x4 w1, bf16* MIX, ss_t* ssb, int lane) {
;     ...
;     for (int t = 0; t < 10; ++t) {
;         constexpr int dummy = 0; (void)dummy;
;         const int rel = t - PAR;
;         if (rel < 0 || rel > 8) { sc[t] = (f32x4){0.f, 0.f, 0.f, 0.f}; continue; }
;         const bf16* kp = KS + (16 * (tb + t) + fr) * KS_STRIDE + 8 * fq;
;         const bf16x8 k0 = *(const bf16x8*)kp, k1 = *(const bf16x8*)(kp + 32);
;         f32x4 acc = (f32x4){0.f, 0.f, 0.f, 0.f};
;         acc = MFMA16(k0, qf[0], acc); acc = MFMA16(k1, qf[1], acc);
;         const bool tv = (n > 0) || (tb + t >= 8);
; #pragma unroll
;         for (int r = 0; r < 4; ++r) { bool valid = tv; if (rel == 0) valid = valid && (e0 + r >= 1); if (rel == 8) valid = valid && (e0 + r <= 0);
;             const float v = valid ? acc[r] + bp[16 * (8 - rel) + (3 - r)] : -1e30f; acc[r] = v; mx = fmaxf(mx, v); }
;         sc[t] = acc;
	ds_read2_b32 v[72:73], v186 offset0:51 offset1:50
	ds_read2_b32 v[74:75], v186 offset0:49 offset1:48
	ds_read2_b32 v[148:149], v186 offset0:35 offset1:34
	ds_read2_b32 v[150:151], v186 offset0:33 offset1:32
	ds_read2_b32 v[152:153], v186 offset0:19 offset1:18
	ds_read2_b32 v[154:155], v186 offset0:17 offset1:16
	ds_read2_b32 v[156:157], v186 offset0:3 offset1:2
	ds_read2_b32 v[158:159], v186 offset0:1 offset1:0
	s_waitcnt lgkmcnt(0)
	v_cndmask_b32_e64 v84, v195, v84, s[40:41]
	v_cndmask_b32_e64 v156, v156, v195, s[40:41]
	v_cndmask_b32_e64 v85, v195, v85, s[42:43]
	v_cndmask_b32_e64 v157, v157, v195, s[42:43]
	v_cndmask_b32_e64 v86, v195, v86, s[44:45]
	v_cndmask_b32_e64 v158, v158, v195, s[44:45]
	v_cndmask_b32_e64 v87, v195, v87, s[46:47]
	v_cndmask_b32_e64 v159, v159, v195, s[46:47]
	ds_read_b128 v[212:215], v185 offset:0
	ds_read_b128 v[216:219], v185 offset:64
	ds_read_b128 v[220:223], v185 offset:2304
	ds_read_b128 v[224:227], v185 offset:2368
	ds_read_b128 v[228:231], v185 offset:4608
	ds_read_b128 v[232:235], v185 offset:4672
	ds_read_b128 v[48:51], v185 offset:6912
	ds_read_b128 v[52:55], v185 offset:6976
	ds_read_b128 v[56:59], v185 offset:9216
	ds_read_b128 v[60:63], v185 offset:9280
	ds_read_b128 v[64:67], v185 offset:11520
	ds_read_b128 v[68:71], v185 offset:11584
	s_waitcnt lgkmcnt(6)
	v_mfma_f32_16x16x32_bf16 v[4:7], v[212:215], v[116:119], v[84:87]
	v_mfma_f32_16x16x32_bf16 v[8:11], v[220:223], v[116:119], v[88:91]
	v_mfma_f32_16x16x32_bf16 v[12:15], v[228:231], v[116:119], v[92:95]
	v_mfma_f32_16x16x32_bf16 v[4:7], v[216:219], v[120:123], v[4:7]
	v_mfma_f32_16x16x32_bf16 v[8:11], v[224:227], v[120:123], v[8:11]
	v_mfma_f32_16x16x32_bf16 v[12:15], v[232:235], v[120:123], v[12:15]
	ds_read_b128 v[212:215], v185 offset:13824
	ds_read_b128 v[216:219], v185 offset:13888
	ds_read_b128 v[220:223], v185 offset:16128
	ds_read_b128 v[224:227], v185 offset:16192
	ds_read_b128 v[228:231], v185 offset:18432
	ds_read_b128 v[232:235], v185 offset:18496
	s_waitcnt lgkmcnt(6)
	v_mfma_f32_16x16x32_bf16 v[16:19], v[48:51], v[116:119], v[96:99]
	v_mfma_f32_16x16x32_bf16 v[20:23], v[56:59], v[116:119], v[40:43]
	v_mfma_f32_16x16x32_bf16 v[24:27], v[64:67], v[116:119], v[72:75]
	v_mfma_f32_16x16x32_bf16 v[16:19], v[52:55], v[120:123], v[16:19]
	v_mfma_f32_16x16x32_bf16 v[20:23], v[60:63], v[120:123], v[20:23]
	v_mfma_f32_16x16x32_bf16 v[24:27], v[68:71], v[120:123], v[24:27]
	s_cmp_lg_u64 s[36:37], 0
	s_cbranch_scc1 .Lat2_nofix_0_0
	s_add_i32 s27, s26, 0
	s_cmp_ge_i32 s27, 8
	s_cbranch_scc1 .Lat2_ok_0_0
	v_mov_b32_e32 v4, v195
	v_mov_b32_e32 v5, v195
	v_mov_b32_e32 v6, v195
	v_mov_b32_e32 v7, v195
